# P1 side task: fragment loads made row-contiguous (1 KiB per wave instruction) and transposed into the MFMA layout through a per-wave LDS stage; same operands and accumulation order
# baseline (speedup 1.0000x reference)
; __device__ __forceinline__ void p1_side_task(int c, LAS unsigned char* lds, const bf16_t* XN, const bf16_t* WIN, const float* b_f, float* LF, bf16_t* Kb, bf16_t* Vb, bf16_t* P1b) {
;     ...
;     const size_t lo_ = (size_t)fr * DM + 256 * w + 8 * fq;
;     const bf16_t* P6[6] = {XN + (size_t)(32 * c) * DM + lo_, XN + (size_t)(32 * c + 16) * DM + lo_, XM + lo_, WF + lo_, WIN + (size_t)n0 * DM + lo_, WIN + (size_t)n1 * DM + lo_};
;     bf16x8 fr6[6][8];
; #pragma unroll
;     for (int s = 0; s < 6; ++s)
; #pragma unroll
;         for (int i = 0; i < 8; ++i) fr6[s][i] = *(const bf16x8*)(P6[s] + 32 * i);
;     f32x4 acc[5];
; #pragma unroll
;     for (int g = 0; g < 5; ++g) acc[g] = (f32x4){0.f, 0.f, 0.f, 0.f};
; #pragma unroll
;     for (int i = 0; i < 8; ++i) {
;         acc[0] = __builtin_amdgcn_mfma_f32_16x16x32_bf16(fr6[0][i], fr6[3][i], acc[0], 0, 0, 0);
;         acc[1] = __builtin_amdgcn_mfma_f32_16x16x32_bf16(fr6[1][i], fr6[3][i], acc[1], 0, 0, 0);
;         acc[2] = __builtin_amdgcn_mfma_f32_16x16x32_bf16(fr6[2][i], fr6[3][i], acc[2], 0, 0, 0);
;         acc[3] = __builtin_amdgcn_mfma_f32_16x16x32_bf16(fr6[4][i], fr6[2][i], acc[3], 0, 0, 0);
;         acc[4] = __builtin_amdgcn_mfma_f32_16x16x32_bf16(fr6[5][i], fr6[2][i], acc[4], 0, 0, 0);
.LBB0_423:
	s_ashr_i32 s11, s10, 31
	s_lshr_b32 s30, s37, 6
	s_lshl_b64 s[38:39], s[10:11], 12
	s_add_u32 s82, s4, s38
	s_addc_u32 s83, s5, s39
	s_add_i32 s40, s10, 16
	s_ashr_i32 s41, s40, 31
	s_lshl_b64 s[38:39], s[40:41], 12
	s_add_u32 s84, s4, s38
	s_addc_u32 s85, s5, s39
	v_and_b32_e32 v120, 63, v186
	v_lshrrev_b32_e32 v121, 5, v120
	v_and_b32_e32 v120, 31, v120
	v_lshlrev_b32_e32 v110, 12, v121
	v_lshl_add_u32 v110, v120, 4, v110
	s_lshl_b32 s86, s30, 9
	v_add_u32_e32 v110, s86, v110
	v_add_u32_e32 v111, 0x2000, v110
	v_add_u32_e32 v112, 0x4000, v110
	v_add_u32_e32 v113, 0x6000, v110
	v_add_u32_e32 v114, 0x8000, v110
	v_add_u32_e32 v115, 0xa000, v110
	v_add_u32_e32 v116, 0xc000, v110
	v_add_u32_e32 v117, 0xe000, v110
	s_mul_i32 s86, s30, 0x2100
	s_add_i32 s86, s86, 0x10000
	v_mul_u32_u24_e32 v118, 0x210, v121
	v_lshl_add_u32 v118, v120, 4, v118
	v_add_u32_e32 v118, s86, v118
	v_and_b32_e32 v120, 15, v186
	v_bfe_u32 v121, v186, 4, 2
	v_mul_u32_u24_e32 v119, 0x210, v120
	v_lshl_add_u32 v119, v121, 4, v119
	v_add_u32_e32 v119, s86, v119
	global_load_dwordx4 v[24:27], v110, s[8:9]
	global_load_dwordx4 v[28:31], v111, s[8:9]
	global_load_dwordx4 v[32:35], v112, s[8:9]
	global_load_dwordx4 v[36:39], v113, s[8:9]
	global_load_dwordx4 v[40:43], v114, s[8:9]
	global_load_dwordx4 v[44:47], v115, s[8:9]
	global_load_dwordx4 v[48:51], v116, s[8:9]
	global_load_dwordx4 v[52:55], v117, s[8:9]
	global_load_dwordx4 v[56:59], v110, s[82:83]
	global_load_dwordx4 v[60:63], v111, s[82:83]
	global_load_dwordx4 v[82:85], v112, s[82:83]
	global_load_dwordx4 v[86:89], v113, s[82:83]
	global_load_dwordx4 v[162:165], v114, s[82:83]
	global_load_dwordx4 v[166:169], v115, s[82:83]
	global_load_dwordx4 v[170:173], v116, s[82:83]
	global_load_dwordx4 v[174:177], v117, s[82:83]
	global_load_dwordx4 v[178:181], v110, s[84:85]
	global_load_dwordx4 v[182:185], v111, s[84:85]
	global_load_dwordx4 v[188:191], v112, s[84:85]
	global_load_dwordx4 v[192:195], v113, s[84:85]
	global_load_dwordx4 v[196:199], v114, s[84:85]
	global_load_dwordx4 v[200:203], v115, s[84:85]
	global_load_dwordx4 v[204:207], v116, s[84:85]
	global_load_dwordx4 v[208:211], v117, s[84:85]
	global_load_dwordx4 v[212:215], v110, s[2:3]
	global_load_dwordx4 v[216:219], v111, s[2:3]
	global_load_dwordx4 v[220:223], v112, s[2:3]
	global_load_dwordx4 v[224:227], v113, s[2:3]
	global_load_dwordx4 v[228:231], v114, s[2:3]
	global_load_dwordx4 v[232:235], v115, s[2:3]
	global_load_dwordx4 v[236:239], v116, s[2:3]
	global_load_dwordx4 v[240:243], v117, s[2:3]
	v_readlane_b32 s40, v248, 29
	v_readlane_b32 s41, v248, 30
	v_readlane_b32 s42, v248, 31
	v_readlane_b32 s43, v248, 32
	v_readlane_b32 s44, v248, 33
	v_readlane_b32 s45, v248, 34
	s_ashr_i32 s29, s28, 31
	v_readlane_b32 s46, v248, 35
	v_readlane_b32 s47, v248, 36
	s_mov_b64 s[40:41], s[44:45]
	s_lshl_b64 s[28:29], s[28:29], 12
	s_mov_b64 s[42:43], s[46:47]
	s_add_u32 s28, s42, s28
	s_addc_u32 s29, s43, s29
	s_ashr_i32 s27, s26, 31
	s_lshl_b64 s[26:27], s[26:27], 12
	s_add_u32 s26, s42, s26
	s_addc_u32 s27, s43, s27
	s_mulk_i32 s30, 0x1400
	v_add_u32_e32 v20, s30, v91
	s_waitcnt vmcnt(24)
	ds_write_b128 v118, v[24:27]
	ds_write_b128 v118, v[28:31] offset:1056
	ds_write_b128 v118, v[32:35] offset:2112
	ds_write_b128 v118, v[36:39] offset:3168
	ds_write_b128 v118, v[40:43] offset:4224
	ds_write_b128 v118, v[44:47] offset:5280
	ds_write_b128 v118, v[48:51] offset:6336
	ds_write_b128 v118, v[52:55] offset:7392
	s_waitcnt lgkmcnt(0)
	ds_read_b128 v[24:27], v119
	ds_read_b128 v[28:31], v119 offset:64
	ds_read_b128 v[32:35], v119 offset:128
	ds_read_b128 v[36:39], v119 offset:192
	ds_read_b128 v[40:43], v119 offset:256
	ds_read_b128 v[44:47], v119 offset:320
	ds_read_b128 v[48:51], v119 offset:384
	ds_read_b128 v[52:55], v119 offset:448
	s_waitcnt lgkmcnt(0)
	s_waitcnt vmcnt(16)
	ds_write_b128 v118, v[56:59]
	ds_write_b128 v118, v[60:63] offset:1056
	ds_write_b128 v118, v[82:85] offset:2112
	ds_write_b128 v118, v[86:89] offset:3168
	ds_write_b128 v118, v[162:165] offset:4224
	ds_write_b128 v118, v[166:169] offset:5280
	ds_write_b128 v118, v[170:173] offset:6336
	ds_write_b128 v118, v[174:177] offset:7392
	s_waitcnt lgkmcnt(0)
	ds_read_b128 v[56:59], v119
	ds_read_b128 v[60:63], v119 offset:64
	ds_read_b128 v[82:85], v119 offset:128
	ds_read_b128 v[86:89], v119 offset:192
	ds_read_b128 v[162:165], v119 offset:256
	ds_read_b128 v[166:169], v119 offset:320
	ds_read_b128 v[170:173], v119 offset:384
	ds_read_b128 v[174:177], v119 offset:448
	s_waitcnt lgkmcnt(0)
	v_mfma_f32_16x16x32_bf16 v[0:3], v[56:59], v[24:27], 0
	v_mfma_f32_16x16x32_bf16 v[0:3], v[60:63], v[28:31], v[0:3]
	v_mfma_f32_16x16x32_bf16 v[0:3], v[82:85], v[32:35], v[0:3]
	v_mfma_f32_16x16x32_bf16 v[0:3], v[86:89], v[36:39], v[0:3]
	v_mfma_f32_16x16x32_bf16 v[0:3], v[162:165], v[40:43], v[0:3]
	v_mfma_f32_16x16x32_bf16 v[0:3], v[166:169], v[44:47], v[0:3]
	v_mfma_f32_16x16x32_bf16 v[0:3], v[170:173], v[48:51], v[0:3]
	v_mfma_f32_16x16x32_bf16 v[0:3], v[174:177], v[52:55], v[0:3]
	s_nop 3
	global_load_dwordx4 v[56:59], v110, s[28:29]
	global_load_dwordx4 v[60:63], v111, s[28:29]
	global_load_dwordx4 v[82:85], v112, s[28:29]
	global_load_dwordx4 v[86:89], v113, s[28:29]
	global_load_dwordx4 v[162:165], v114, s[28:29]
	global_load_dwordx4 v[166:169], v115, s[28:29]
	global_load_dwordx4 v[170:173], v116, s[28:29]
	global_load_dwordx4 v[174:177], v117, s[28:29]
	s_waitcnt vmcnt(16)
	ds_write_b128 v118, v[178:181]
	ds_write_b128 v118, v[182:185] offset:1056
	ds_write_b128 v118, v[188:191] offset:2112
	ds_write_b128 v118, v[192:195] offset:3168
	ds_write_b128 v118, v[196:199] offset:4224
	ds_write_b128 v118, v[200:203] offset:5280
	ds_write_b128 v118, v[204:207] offset:6336
	ds_write_b128 v118, v[208:211] offset:7392
	s_waitcnt lgkmcnt(0)
; #define LAS __attribute__((address_space(3)))
; __device__ __forceinline__ void p1_side_task(int c, LAS unsigned char* lds, const bf16_t* XN, const bf16_t* WIN, const float* b_f, float* LF, bf16_t* Kb, bf16_t* Vb, bf16_t* P1b) {
;     ...
;     for (int i = 0; i < 8; ++i) {
;         acc[0] = __builtin_amdgcn_mfma_f32_16x16x32_bf16(fr6[0][i], fr6[3][i], acc[0], 0, 0, 0);
;         acc[1] = __builtin_amdgcn_mfma_f32_16x16x32_bf16(fr6[1][i], fr6[3][i], acc[1], 0, 0, 0);
;         acc[2] = __builtin_amdgcn_mfma_f32_16x16x32_bf16(fr6[2][i], fr6[3][i], acc[2], 0, 0, 0);
;         acc[3] = __builtin_amdgcn_mfma_f32_16x16x32_bf16(fr6[4][i], fr6[2][i], acc[3], 0, 0, 0);
;         acc[4] = __builtin_amdgcn_mfma_f32_16x16x32_bf16(fr6[5][i], fr6[2][i], acc[4], 0, 0, 0);
;     }
;     LAS f32x4* red = (LAS f32x4*)lds;
; #pragma unroll
;     for (int g = 0; g < 5; ++g) red[(w * 5 + g) * 64 + lane] = acc[g];
;     __syncthreads();
	ds_read_b128 v[178:181], v119
	ds_read_b128 v[182:185], v119 offset:64
	ds_read_b128 v[188:191], v119 offset:128
	ds_read_b128 v[192:195], v119 offset:192
	ds_read_b128 v[196:199], v119 offset:256
	ds_read_b128 v[200:203], v119 offset:320
	ds_read_b128 v[204:207], v119 offset:384
	ds_read_b128 v[208:211], v119 offset:448
	s_waitcnt lgkmcnt(0)
	v_mfma_f32_16x16x32_bf16 v[4:7], v[178:181], v[24:27], 0
	v_mfma_f32_16x16x32_bf16 v[4:7], v[182:185], v[28:31], v[4:7]
	v_mfma_f32_16x16x32_bf16 v[4:7], v[188:191], v[32:35], v[4:7]
	v_mfma_f32_16x16x32_bf16 v[4:7], v[192:195], v[36:39], v[4:7]
	v_mfma_f32_16x16x32_bf16 v[4:7], v[196:199], v[40:43], v[4:7]
	v_mfma_f32_16x16x32_bf16 v[4:7], v[200:203], v[44:47], v[4:7]
	v_mfma_f32_16x16x32_bf16 v[4:7], v[204:207], v[48:51], v[4:7]
	v_mfma_f32_16x16x32_bf16 v[4:7], v[208:211], v[52:55], v[4:7]
	s_nop 3
	global_load_dwordx4 v[178:181], v110, s[26:27]
	global_load_dwordx4 v[182:185], v111, s[26:27]
	global_load_dwordx4 v[188:191], v112, s[26:27]
	global_load_dwordx4 v[192:195], v113, s[26:27]
	global_load_dwordx4 v[196:199], v114, s[26:27]
	global_load_dwordx4 v[200:203], v115, s[26:27]
	global_load_dwordx4 v[204:207], v116, s[26:27]
	global_load_dwordx4 v[208:211], v117, s[26:27]
	s_waitcnt vmcnt(16)
	ds_write_b128 v118, v[212:215]
	ds_write_b128 v118, v[216:219] offset:1056
	ds_write_b128 v118, v[220:223] offset:2112
	ds_write_b128 v118, v[224:227] offset:3168
	ds_write_b128 v118, v[228:231] offset:4224
	ds_write_b128 v118, v[232:235] offset:5280
	ds_write_b128 v118, v[236:239] offset:6336
	ds_write_b128 v118, v[240:243] offset:7392
	s_waitcnt lgkmcnt(0)
	ds_read_b128 v[212:215], v119
	ds_read_b128 v[216:219], v119 offset:64
	ds_read_b128 v[220:223], v119 offset:128
	ds_read_b128 v[224:227], v119 offset:192
	ds_read_b128 v[228:231], v119 offset:256
	ds_read_b128 v[232:235], v119 offset:320
	ds_read_b128 v[236:239], v119 offset:384
	ds_read_b128 v[240:243], v119 offset:448
	s_waitcnt lgkmcnt(0)
	v_mfma_f32_16x16x32_bf16 v[8:11], v[212:215], v[24:27], 0
	v_mfma_f32_16x16x32_bf16 v[8:11], v[216:219], v[28:31], v[8:11]
	v_mfma_f32_16x16x32_bf16 v[8:11], v[220:223], v[32:35], v[8:11]
	v_mfma_f32_16x16x32_bf16 v[8:11], v[224:227], v[36:39], v[8:11]
	v_mfma_f32_16x16x32_bf16 v[8:11], v[228:231], v[40:43], v[8:11]
	v_mfma_f32_16x16x32_bf16 v[8:11], v[232:235], v[44:47], v[8:11]
	v_mfma_f32_16x16x32_bf16 v[8:11], v[236:239], v[48:51], v[8:11]
	v_mfma_f32_16x16x32_bf16 v[8:11], v[240:243], v[52:55], v[8:11]
	s_waitcnt vmcnt(8)
	ds_write_b128 v118, v[56:59]
	ds_write_b128 v118, v[60:63] offset:1056
	ds_write_b128 v118, v[82:85] offset:2112
	ds_write_b128 v118, v[86:89] offset:3168
	ds_write_b128 v118, v[162:165] offset:4224
	ds_write_b128 v118, v[166:169] offset:5280
	ds_write_b128 v118, v[170:173] offset:6336
	ds_write_b128 v118, v[174:177] offset:7392
	s_waitcnt lgkmcnt(0)
	ds_read_b128 v[56:59], v119
	ds_read_b128 v[60:63], v119 offset:64
	ds_read_b128 v[82:85], v119 offset:128
	ds_read_b128 v[86:89], v119 offset:192
	ds_read_b128 v[162:165], v119 offset:256
	ds_read_b128 v[166:169], v119 offset:320
	ds_read_b128 v[170:173], v119 offset:384
	ds_read_b128 v[174:177], v119 offset:448
	s_waitcnt lgkmcnt(0)
	v_mfma_f32_16x16x32_bf16 v[12:15], v[56:59], v[212:215], 0
	v_mfma_f32_16x16x32_bf16 v[12:15], v[60:63], v[216:219], v[12:15]
	v_mfma_f32_16x16x32_bf16 v[12:15], v[82:85], v[220:223], v[12:15]
	v_mfma_f32_16x16x32_bf16 v[12:15], v[86:89], v[224:227], v[12:15]
	v_mfma_f32_16x16x32_bf16 v[12:15], v[162:165], v[228:231], v[12:15]
	v_mfma_f32_16x16x32_bf16 v[12:15], v[166:169], v[232:235], v[12:15]
	v_mfma_f32_16x16x32_bf16 v[12:15], v[170:173], v[236:239], v[12:15]
	v_mfma_f32_16x16x32_bf16 v[12:15], v[174:177], v[240:243], v[12:15]
	s_waitcnt vmcnt(0)
	ds_write_b128 v118, v[178:181]
	ds_write_b128 v118, v[182:185] offset:1056
	ds_write_b128 v118, v[188:191] offset:2112
	ds_write_b128 v118, v[192:195] offset:3168
	ds_write_b128 v118, v[196:199] offset:4224
	ds_write_b128 v118, v[200:203] offset:5280
	ds_write_b128 v118, v[204:207] offset:6336
	ds_write_b128 v118, v[208:211] offset:7392
	s_waitcnt lgkmcnt(0)
	ds_read_b128 v[178:181], v119
	ds_read_b128 v[182:185], v119 offset:64
	ds_read_b128 v[188:191], v119 offset:128
	ds_read_b128 v[192:195], v119 offset:192
	ds_read_b128 v[196:199], v119 offset:256
	ds_read_b128 v[200:203], v119 offset:320
	ds_read_b128 v[204:207], v119 offset:384
	ds_read_b128 v[208:211], v119 offset:448
	s_waitcnt lgkmcnt(0)
	v_mfma_f32_16x16x32_bf16 v[16:19], v[178:181], v[212:215], 0
	v_mfma_f32_16x16x32_bf16 v[16:19], v[182:185], v[216:219], v[16:19]
	v_mfma_f32_16x16x32_bf16 v[16:19], v[188:191], v[220:223], v[16:19]
	v_mfma_f32_16x16x32_bf16 v[16:19], v[192:195], v[224:227], v[16:19]
	v_mfma_f32_16x16x32_bf16 v[16:19], v[196:199], v[228:231], v[16:19]
	v_mfma_f32_16x16x32_bf16 v[16:19], v[200:203], v[232:235], v[16:19]
	v_mfma_f32_16x16x32_bf16 v[16:19], v[204:207], v[236:239], v[16:19]
	v_mfma_f32_16x16x32_bf16 v[16:19], v[208:211], v[240:243], v[16:19]
	s_cmp_gt_u32 s37, 63
	s_nop 7
	s_nop 7
	s_nop 3
	ds_write_b128 v20, v[0:3]
	ds_write_b128 v20, v[4:7] offset:1024
	ds_write_b128 v20, v[8:11] offset:2048
	ds_write_b128 v20, v[12:15] offset:3072
	ds_write_b128 v20, v[16:19] offset:4096
	s_waitcnt lgkmcnt(0)
	s_barrier
	s_cbranch_scc1 .LBB0_414
; __device__ __forceinline__ void p1_side_task(int c, LAS unsigned char* lds, const bf16_t* XN, const bf16_t* WIN, const float* b_f, float* LF, bf16_t* Kb, bf16_t* Vb, bf16_t* P1b) {
;     ...
;     if (w == 0) {
; #pragma unroll
;         for (int g = 0; g < 5; ++g) { f32x4 s = red[g * 64 + lane];
; #pragma unroll
;             for (int ww = 1; ww < 8; ++ww) s += red[(ww * 5 + g) * 64 + lane];
;             acc[g] = s; }
;         const float bfh = b_f[fr];
; #pragma unroll
;         for (int g = 0; g < 3; ++g)
; #pragma unroll
;             for (int j = 0; j < 4; ++j) { const float xx = acc[g][j] + bfh; const float v = (fminf(xx, 0.f) - log1pf(__expf(-fabsf(xx)))) * LOG2E; const int m = 4 * fq + j;
;                 if (g < 2) { const int row = 32 * c + 16 * g + m; LF[(size_t)((row >> 12) * NH + fr) * KVROWS + 64 + (row & 4095)] = v; }
	global_load_dword v97, v[66:67], off
	ds_read_b128 v[82:85], v91
	ds_read_b128 v[98:101], v91 offset:1024
	ds_read_b128 v[102:105], v91 offset:5120
	ds_read_b128 v[106:109], v91 offset:6144
	ds_read_b128 v[110:113], v91 offset:10240
	ds_read_b128 v[114:117], v91 offset:11264
	ds_read_b128 v[118:121], v91 offset:15360
	ds_read_b128 v[122:125], v91 offset:16384
	ds_read_b128 v[126:129], v91 offset:20480
	ds_read_b128 v[130:133], v91 offset:21504
	ds_read_b128 v[138:141], v91 offset:25600
	ds_read_b128 v[142:145], v91 offset:26624
	ds_read_b128 v[146:149], v91 offset:30720
	ds_read_b128 v[150:153], v91 offset:31744
	ds_read_b128 v[154:157], v91 offset:35840
	ds_read_b128 v[158:161], v91 offset:36864
	ds_read_b128 v[52:55], v91 offset:3072
	ds_read_b128 v[20:23], v91 offset:4096
	ds_read_b128 v[60:63], v91 offset:8192
	ds_read_b128 v[28:31], v91 offset:9216
	ds_read_b128 v[56:59], v91 offset:13312
	ds_read_b128 v[24:27], v91 offset:14336
	ds_read_b128 v[48:51], v91 offset:18432
	ds_read_b128 v[16:19], v91 offset:19456
	ds_read_b128 v[44:47], v91 offset:23552
	ds_read_b128 v[12:15], v91 offset:24576
	ds_read_b128 v[40:43], v91 offset:28672
	ds_read_b128 v[8:11], v91 offset:29696
	ds_read_b128 v[36:39], v91 offset:33792
	ds_read_b128 v[4:7], v91 offset:34816
	ds_read_b128 v[32:35], v91 offset:38912
	ds_read_b128 v[0:3], v91 offset:39936
	s_waitcnt lgkmcnt(14)
	v_pk_add_f32 v[84:85], v[84:85], v[104:105]
	v_pk_add_f32 v[82:83], v[82:83], v[102:103]
	v_pk_add_f32 v[84:85], v[84:85], v[112:113]
	v_pk_add_f32 v[82:83], v[82:83], v[110:111]
	v_pk_add_f32 v[88:89], v[100:101], v[108:109]
	v_pk_add_f32 v[98:99], v[98:99], v[106:107]
	v_pk_add_f32 v[84:85], v[84:85], v[120:121]
	v_pk_add_f32 v[82:83], v[82:83], v[118:119]
	v_pk_add_f32 v[88:89], v[88:89], v[116:117]
	v_pk_add_f32 v[98:99], v[98:99], v[114:115]
	v_pk_add_f32 v[84:85], v[84:85], v[128:129]
	v_pk_add_f32 v[82:83], v[82:83], v[126:127]
	v_pk_add_f32 v[88:89], v[88:89], v[124:125]
	v_pk_add_f32 v[98:99], v[98:99], v[122:123]
	v_pk_add_f32 v[84:85], v[84:85], v[140:141]
	v_pk_add_f32 v[82:83], v[82:83], v[138:139]
	v_pk_add_f32 v[88:89], v[88:89], v[132:133]
	v_pk_add_f32 v[98:99], v[98:99], v[130:131]
	v_pk_add_f32 v[84:85], v[84:85], v[148:149]
	v_pk_add_f32 v[82:83], v[82:83], v[146:147]
	v_pk_add_f32 v[88:89], v[88:89], v[144:145]
	v_pk_add_f32 v[98:99], v[98:99], v[142:143]
	v_pk_add_f32 v[100:101], v[84:85], v[156:157]
	v_pk_add_f32 v[84:85], v[82:83], v[154:155]
	v_pk_add_f32 v[88:89], v[88:89], v[152:153]
	v_pk_add_f32 v[98:99], v[98:99], v[150:151]
	v_pk_add_f32 v[82:83], v[88:89], v[160:161]
	v_pk_add_f32 v[88:89], v[98:99], v[158:159]
	s_lshr_b32 s11, s10, 8
	s_and_b32 s26, s10, 0xfe0
	s_and_b32 s11, s11, 0xfffff0
	v_or_b32_e32 v64, s26, v92
	v_or_b32_e32 v86, s11, v136
	v_readlane_b32 s26, v248, 52
	v_mul_hi_i32_i24_e32 v87, 0x4100, v86
	v_mul_i32_i24_e32 v86, 0x4100, v86
	v_readlane_b32 s27, v248, 53
	v_lshlrev_b32_e32 v64, 2, v64
	s_cmp_lg_u32 s36, 0
	v_lshl_add_u64 v[86:87], s[26:27], 0, v[86:87]
	v_lshl_add_u64 v[86:87], v[86:87], 0, v[64:65]
	s_waitcnt vmcnt(0)
	v_add_f32_e32 v84, v84, v97
	v_add_f32_e32 v85, v85, v97
	v_mul_f32_e64 v98, |v84|, s19
	v_mul_f32_e64 v99, |v85|, s19
	v_exp_f32_e32 v130, v98
	v_exp_f32_e32 v131, v99
	v_min_f32_e32 v98, 0, v84
	v_min_f32_e32 v99, 0, v85
	v_add_f32_e32 v104, 1.0, v130
	v_add_f32_e32 v106, 1.0, v131
	v_cvt_f64_f32_e32 v[84:85], v104
	v_add_f32_e32 v107, -1.0, v104
	v_cvt_f64_f32_e32 v[102:103], v106
	v_frexp_exp_i32_f64_e32 v84, v[84:85]
	v_sub_f32_e32 v85, v130, v107
	v_sub_f32_e32 v107, v107, v104
	v_frexp_exp_i32_f64_e32 v102, v[102:103]
	v_add_f32_e32 v103, 1.0, v107
	v_add_f32_e32 v85, v85, v103
	v_add_f32_e32 v103, -1.0, v106
	v_frexp_mant_f32_e32 v108, v106
	v_sub_f32_e32 v107, v131, v103
	v_sub_f32_e32 v103, v103, v106
	v_add_f32_e32 v103, 1.0, v103
	v_cmp_gt_f32_e32 vcc, s21, v108
	v_frexp_mant_f32_e32 v105, v104
	v_add_f32_e32 v103, v107, v103
	v_subbrev_co_u32_e32 v107, vcc, 0, v102, vcc
	v_cmp_gt_f32_e32 vcc, s21, v105
	v_cvt_f32_i32_e32 v105, v107
	v_sub_u32_e32 v107, 0, v107
	v_subbrev_co_u32_e32 v108, vcc, 0, v84, vcc
	v_sub_u32_e32 v102, 0, v108
	v_ldexp_f32 v84, v104, v102
	v_ldexp_f32 v102, v85, v102
	v_ldexp_f32 v85, v106, v107
	v_pk_add_f32 v[116:117], v[84:85], 1.0 op_sel_hi:[1,0]
	v_ldexp_f32 v103, v103, v107
	v_pk_add_f32 v[118:119], v[116:117], -1.0 op_sel_hi:[1,0]
	v_pk_add_f32 v[112:113], v[84:85], -1.0 op_sel_hi:[1,0]
	v_pk_add_f32 v[118:119], v[84:85], v[118:119] neg_lo:[0,1] neg_hi:[0,1]
	v_pk_add_f32 v[114:115], v[112:113], 1.0 op_sel_hi:[1,0]
	v_pk_add_f32 v[118:119], v[102:103], v[118:119]
	v_pk_add_f32 v[84:85], v[84:85], v[114:115] neg_lo:[0,1] neg_hi:[0,1]
	v_pk_add_f32 v[120:121], v[116:117], v[118:119]
	v_pk_add_f32 v[84:85], v[102:103], v[84:85]
	v_rcp_f32_e32 v122, v120
	v_rcp_f32_e32 v123, v121
	v_pk_add_f32 v[102:103], v[112:113], v[84:85]
	v_pk_add_f32 v[116:117], v[120:121], v[116:117] neg_lo:[0,1] neg_hi:[0,1]
	v_pk_add_f32 v[112:113], v[102:103], v[112:113] neg_lo:[0,1] neg_hi:[0,1]
	v_pk_mul_f32 v[114:115], v[102:103], v[122:123]
	v_pk_add_f32 v[116:117], v[118:119], v[116:117] neg_lo:[0,1] neg_hi:[0,1]
	v_pk_mul_f32 v[124:125], v[120:121], v[114:115]
	v_pk_add_f32 v[84:85], v[84:85], v[112:113] neg_lo:[0,1] neg_hi:[0,1]
	v_pk_fma_f32 v[118:119], v[114:115], v[120:121], v[124:125] neg_lo:[0,0,1] neg_hi:[0,0,1]
	v_cvt_f32_i32_e32 v104, v108
	v_pk_fma_f32 v[118:119], v[114:115], v[116:117], v[118:119]
	v_cmp_neq_f32_e32 vcc, s33, v130
	v_pk_add_f32 v[126:127], v[124:125], v[118:119]
	v_pk_mul_f32 v[106:107], v[104:105], s[12:13] op_sel_hi:[1,0]
	v_pk_add_f32 v[128:129], v[102:103], v[126:127] neg_lo:[0,1] neg_hi:[0,1]
; __device__ __forceinline__ void p1_side_task(int c, LAS unsigned char* lds, const bf16_t* XN, const bf16_t* WIN, const float* b_f, float* LF, bf16_t* Kb, bf16_t* Vb, bf16_t* P1b) {
;     ...
;             for (int j = 0; j < 4; ++j) { const float xx = acc[g][j] + bfh; const float v = (fminf(xx, 0.f) - log1pf(__expf(-fabsf(xx)))) * LOG2E; const int m = 4 * fq + j;
;                 if (g < 2) { const int row = 32 * c + 16 * g + m; LF[(size_t)((row >> 12) * NH + fr) * KVROWS + 64 + (row & 4095)] = v; }
	v_pk_add_f32 v[124:125], v[126:127], v[124:125] neg_lo:[0,1] neg_hi:[0,1]
	v_pk_add_f32 v[102:103], v[102:103], v[128:129] neg_lo:[0,1] neg_hi:[0,1]
	v_pk_add_f32 v[118:119], v[124:125], v[118:119] neg_lo:[0,1] neg_hi:[0,1]
	v_pk_add_f32 v[102:103], v[102:103], v[126:127] neg_lo:[0,1] neg_hi:[0,1]
	v_pk_fma_f32 v[108:109], v[104:105], s[12:13], v[106:107] op_sel_hi:[1,0,1] neg_lo:[0,0,1] neg_hi:[0,0,1]
	v_pk_add_f32 v[84:85], v[84:85], v[102:103]
	v_pk_fma_f32 v[104:105], v[104:105], s[14:15], v[108:109] op_sel_hi:[1,0,1]
	v_pk_add_f32 v[84:85], v[118:119], v[84:85]
	v_pk_add_f32 v[108:109], v[106:107], v[104:105]
	v_pk_add_f32 v[102:103], v[128:129], v[84:85]
	v_pk_add_f32 v[110:111], v[108:109], v[106:107] neg_lo:[0,1] neg_hi:[0,1]
	v_pk_mul_f32 v[112:113], v[122:123], v[102:103]
	v_mov_b32_e32 v106, v108
	v_pk_mul_f32 v[118:119], v[120:121], v[112:113]
	v_pk_add_f32 v[124:125], v[114:115], v[112:113]
	v_pk_fma_f32 v[120:121], v[112:113], v[120:121], v[118:119] neg_lo:[0,0,1] neg_hi:[0,0,1]
	v_pk_add_f32 v[114:115], v[124:125], v[114:115] neg_lo:[0,1] neg_hi:[0,1]
	v_add_f32_e32 v100, v100, v97
	v_pk_add_f32 v[114:115], v[112:113], v[114:115] neg_lo:[0,1] neg_hi:[0,1]
	v_pk_fma_f32 v[112:113], v[112:113], v[116:117], v[120:121]
	v_add_f32_e32 v101, v101, v97
	v_pk_add_f32 v[116:117], v[118:119], v[112:113]
	v_add_f32_e32 v89, v89, v97
	v_pk_add_f32 v[120:121], v[102:103], v[116:117] neg_lo:[0,1] neg_hi:[0,1]
	v_pk_add_f32 v[118:119], v[116:117], v[118:119] neg_lo:[0,1] neg_hi:[0,1]
	v_add_f32_e32 v83, v83, v97
	v_pk_add_f32 v[112:113], v[118:119], v[112:113] neg_lo:[0,1] neg_hi:[0,1]
	v_pk_add_f32 v[118:119], v[128:129], v[102:103] neg_lo:[0,1] neg_hi:[0,1]
	v_pk_add_f32 v[102:103], v[102:103], v[120:121] neg_lo:[0,1] neg_hi:[0,1]
	v_pk_add_f32 v[84:85], v[84:85], v[118:119]
	v_pk_add_f32 v[102:103], v[102:103], v[116:117] neg_lo:[0,1] neg_hi:[0,1]
	s_nop 0
	v_pk_add_f32 v[84:85], v[84:85], v[102:103]
	s_nop 0
	v_pk_add_f32 v[84:85], v[112:113], v[84:85]
	s_nop 0
	v_pk_add_f32 v[84:85], v[120:121], v[84:85]
	v_mov_b32_e32 v121, v109
	v_pk_mul_f32 v[84:85], v[122:123], v[84:85]
	s_nop 0
	v_pk_add_f32 v[84:85], v[114:115], v[84:85]
	s_nop 0
	v_pk_add_f32 v[102:103], v[124:125], v[84:85]
	s_nop 0
	v_pk_add_f32 v[114:115], v[102:103], v[124:125] neg_lo:[0,1] neg_hi:[0,1]
	v_pk_mul_f32 v[116:117], v[102:103], v[102:103]
	v_pk_add_f32 v[114:115], v[84:85], v[114:115] neg_lo:[0,1] neg_hi:[0,1]
	v_mov_b64_e32 v[84:85], s[16:17]
	v_pk_fma_f32 v[118:119], v[116:117], s[18:19], v[84:85] op_sel_hi:[1,0,0]
	v_ldexp_f32 v112, v102, 1
	v_ldexp_f32 v113, v103, 1
	v_pk_mul_f32 v[102:103], v[102:103], v[116:117]
	v_pk_fma_f32 v[116:117], v[116:117], v[118:119], s[20:21] op_sel_hi:[1,1,0]
	v_ldexp_f32 v114, v114, 1
	v_pk_mul_f32 v[102:103], v[102:103], v[116:117]
	v_ldexp_f32 v115, v115, 1
	v_pk_add_f32 v[116:117], v[112:113], v[102:103]
	s_nop 0
	v_pk_add_f32 v[112:113], v[116:117], v[112:113] neg_lo:[0,1] neg_hi:[0,1]
	s_nop 0
	v_pk_add_f32 v[102:103], v[102:103], v[112:113] neg_lo:[0,1] neg_hi:[0,1]
	s_nop 0
	v_pk_add_f32 v[102:103], v[114:115], v[102:103]
	s_nop 0
	v_pk_add_f32 v[112:113], v[116:117], v[102:103]
	s_nop 0
	v_pk_add_f32 v[118:119], v[108:109], v[112:113]
	v_pk_add_f32 v[114:115], v[112:113], v[116:117] neg_lo:[0,1] neg_hi:[0,1]
	v_mov_b32_e32 v120, v118
	v_pk_add_f32 v[106:107], v[120:121], v[106:107] neg_lo:[0,1] neg_hi:[0,1]
	v_mov_b32_e32 v120, v112
	v_mov_b32_e32 v121, v105
	v_pk_add_f32 v[120:121], v[120:121], v[106:107] neg_lo:[0,1] neg_hi:[0,1]
	v_mov_b32_e32 v111, v107
	v_mov_b32_e32 v112, v118
	v_mov_b32_e32 v107, v117
	v_pk_add_f32 v[106:107], v[112:113], v[106:107] neg_lo:[0,1] neg_hi:[0,1]
	v_mov_b32_e32 v116, v108
	v_mov_b32_e32 v117, v103
	v_mov_b32_e32 v115, v107
	v_pk_add_f32 v[124:125], v[118:119], v[108:109] neg_lo:[0,1] neg_hi:[0,1]
	v_pk_add_f32 v[116:117], v[116:117], v[106:107] neg_lo:[0,1] neg_hi:[0,1]
	v_pk_add_f32 v[106:107], v[102:103], v[114:115] neg_lo:[0,1] neg_hi:[0,1]
	v_mov_b32_e32 v103, v113
	v_pk_add_f32 v[112:113], v[118:119], v[124:125] neg_lo:[0,1] neg_hi:[0,1]
	v_pk_add_f32 v[122:123], v[104:105], v[110:111] neg_lo:[0,1] neg_hi:[0,1]
	v_mov_b32_e32 v115, v125
	v_mov_b32_e32 v105, v109
	v_mov_b32_e32 v111, v113
	v_pk_add_f32 v[102:103], v[102:103], v[114:115] neg_lo:[0,1] neg_hi:[0,1]
	v_pk_add_f32 v[104:105], v[104:105], v[110:111] neg_lo:[0,1] neg_hi:[0,1]
	v_pk_add_f32 v[116:117], v[120:121], v[116:117]
	v_pk_add_f32 v[102:103], v[102:103], v[104:105]
	v_mov_b32_e32 v105, v121
	v_pk_add_f32 v[108:109], v[116:117], v[102:103]
	v_mov_b32_e32 v103, v117
	v_pk_add_f32 v[104:105], v[102:103], v[104:105] neg_lo:[0,1] neg_hi:[0,1]
	v_pk_add_f32 v[110:111], v[118:119], v[108:109]
	v_pk_add_f32 v[102:103], v[102:103], v[104:105] neg_lo:[0,1] neg_hi:[0,1]
	v_pk_add_f32 v[106:107], v[106:107], v[104:105] neg_lo:[0,1] neg_hi:[0,1]
	v_pk_add_f32 v[102:103], v[122:123], v[102:103] neg_lo:[0,1] neg_hi:[0,1]
	v_pk_add_f32 v[104:105], v[110:111], v[118:119] neg_lo:[0,1] neg_hi:[0,1]
	v_pk_add_f32 v[102:103], v[106:107], v[102:103]
	v_pk_add_f32 v[104:105], v[108:109], v[104:105] neg_lo:[0,1] neg_hi:[0,1]
	s_nop 0
	v_pk_add_f32 v[102:103], v[102:103], v[104:105]
	v_mul_f32_e64 v104, |v100|, s19
	v_pk_add_f32 v[102:103], v[110:111], v[102:103]
	v_exp_f32_e32 v132, v104
	v_cndmask_b32_e32 v102, v94, v102, vcc
	v_cmp_neq_f32_e32 vcc, s33, v131
	v_min_f32_e32 v100, 0, v100
	v_add_f32_e32 v104, 1.0, v132
	v_cndmask_b32_e32 v103, v94, v103, vcc
	v_cmp_ngt_f32_e32 vcc, -1.0, v131
	v_frexp_mant_f32_e32 v106, v104
	s_nop 0
	v_cndmask_b32_e32 v103, v95, v103, vcc
	v_cmp_ngt_f32_e32 vcc, -1.0, v130
	s_nop 1
; __device__ __forceinline__ void p1_side_task(int c, LAS unsigned char* lds, const bf16_t* XN, const bf16_t* WIN, const float* b_f, float* LF, bf16_t* Kb, bf16_t* Vb, bf16_t* P1b) {
;     ...
;             for (int j = 0; j < 4; ++j) { const float xx = acc[g][j] + bfh; const float v = (fminf(xx, 0.f) - log1pf(__expf(-fabsf(xx)))) * LOG2E; const int m = 4 * fq + j;
;                 if (g < 2) { const int row = 32 * c + 16 * g + m; LF[(size_t)((row >> 12) * NH + fr) * KVROWS + 64 + (row & 4095)] = v; }
	v_cndmask_b32_e32 v102, v95, v102, vcc
	v_cmp_neq_f32_e32 vcc, -1.0, v130
	s_nop 1
	v_cndmask_b32_e32 v102, v96, v102, vcc
	v_cmp_neq_f32_e32 vcc, -1.0, v131
	s_nop 1
	v_cndmask_b32_e32 v103, v96, v103, vcc
	v_cmp_lt_f32_e64 vcc, |v131|, s23
	s_nop 1
	v_cndmask_b32_e32 v103, v103, v131, vcc
	v_cmp_lt_f32_e64 vcc, |v130|, s23
	s_nop 1
	v_cndmask_b32_e32 v102, v102, v130, vcc
	v_pk_add_f32 v[98:99], v[98:99], v[102:103] neg_lo:[0,1] neg_hi:[0,1]
	v_cvt_f64_f32_e32 v[102:103], v104
	v_frexp_exp_i32_f64_e32 v105, v[102:103]
	v_add_f32_e32 v102, -1.0, v104
	v_sub_f32_e32 v103, v132, v102
	v_sub_f32_e32 v102, v102, v104
	v_add_f32_e32 v102, 1.0, v102
	v_add_f32_e32 v107, v103, v102
	v_mul_f32_e64 v102, |v101|, s19
	v_exp_f32_e32 v133, v102
	v_min_f32_e32 v101, 0, v101
	v_pk_mul_f32 v[98:99], v[98:99], s[22:23] op_sel_hi:[1,0]
	v_add_f32_e32 v64, 1.0, v133
	v_cvt_f64_f32_e32 v[102:103], v64
	v_frexp_exp_i32_f64_e32 v102, v[102:103]
	v_frexp_mant_f32_e32 v103, v64
	v_cmp_gt_f32_e32 vcc, s21, v103
	v_add_f32_e32 v108, -1.0, v64
	v_sub_f32_e32 v109, v133, v108
	v_subbrev_co_u32_e32 v103, vcc, 0, v102, vcc
	v_cmp_gt_f32_e32 vcc, s21, v106
	v_sub_f32_e32 v108, v108, v64
	v_add_f32_e32 v108, 1.0, v108
	v_subbrev_co_u32_e32 v105, vcc, 0, v105, vcc
	v_sub_u32_e32 v106, 0, v105
	v_ldexp_f32 v102, v104, v106
	v_ldexp_f32 v104, v107, v106
	v_cvt_f32_i32_e32 v106, v105
	v_sub_u32_e32 v105, 0, v103
	v_cvt_f32_i32_e32 v107, v103
	v_ldexp_f32 v103, v64, v105
	v_pk_add_f32 v[118:119], v[102:103], 1.0 op_sel_hi:[1,0]
	v_add_f32_e32 v108, v109, v108
	v_pk_add_f32 v[120:121], v[118:119], -1.0 op_sel_hi:[1,0]
	v_ldexp_f32 v105, v108, v105
	v_pk_add_f32 v[120:121], v[102:103], v[120:121] neg_lo:[0,1] neg_hi:[0,1]
	v_pk_add_f32 v[114:115], v[102:103], -1.0 op_sel_hi:[1,0]
	v_pk_add_f32 v[120:121], v[104:105], v[120:121]
	v_pk_add_f32 v[116:117], v[114:115], 1.0 op_sel_hi:[1,0]
	v_pk_add_f32 v[122:123], v[118:119], v[120:121]
	v_pk_add_f32 v[102:103], v[102:103], v[116:117] neg_lo:[0,1] neg_hi:[0,1]
	v_rcp_f32_e32 v124, v122
	v_rcp_f32_e32 v125, v123
	v_pk_add_f32 v[102:103], v[104:105], v[102:103]
	v_pk_add_f32 v[118:119], v[122:123], v[118:119] neg_lo:[0,1] neg_hi:[0,1]
	v_pk_add_f32 v[104:105], v[114:115], v[102:103]
	v_pk_add_f32 v[118:119], v[120:121], v[118:119] neg_lo:[0,1] neg_hi:[0,1]
	v_pk_mul_f32 v[116:117], v[104:105], v[124:125]
	v_pk_add_f32 v[114:115], v[104:105], v[114:115] neg_lo:[0,1] neg_hi:[0,1]
	v_pk_mul_f32 v[126:127], v[122:123], v[116:117]
	v_pk_add_f32 v[102:103], v[102:103], v[114:115] neg_lo:[0,1] neg_hi:[0,1]
	v_pk_fma_f32 v[120:121], v[116:117], v[122:123], v[126:127] neg_lo:[0,0,1] neg_hi:[0,0,1]
	v_pk_mul_f32 v[108:109], v[106:107], s[12:13] op_sel_hi:[1,0]
	v_pk_fma_f32 v[120:121], v[116:117], v[118:119], v[120:121]
	v_pk_fma_f32 v[110:111], v[106:107], s[12:13], v[108:109] op_sel_hi:[1,0,1] neg_lo:[0,0,1] neg_hi:[0,0,1]
	v_pk_add_f32 v[128:129], v[126:127], v[120:121]
	v_pk_fma_f32 v[106:107], v[106:107], s[14:15], v[110:111] op_sel_hi:[1,0,1]
	v_pk_add_f32 v[130:131], v[104:105], v[128:129] neg_lo:[0,1] neg_hi:[0,1]
	v_pk_add_f32 v[126:127], v[128:129], v[126:127] neg_lo:[0,1] neg_hi:[0,1]
	v_pk_add_f32 v[104:105], v[104:105], v[130:131] neg_lo:[0,1] neg_hi:[0,1]
	v_pk_add_f32 v[120:121], v[126:127], v[120:121] neg_lo:[0,1] neg_hi:[0,1]
	v_pk_add_f32 v[104:105], v[104:105], v[128:129] neg_lo:[0,1] neg_hi:[0,1]
	v_pk_add_f32 v[110:111], v[108:109], v[106:107]
	v_pk_add_f32 v[102:103], v[102:103], v[104:105]
	v_pk_add_f32 v[112:113], v[110:111], v[108:109] neg_lo:[0,1] neg_hi:[0,1]
	v_pk_add_f32 v[102:103], v[120:121], v[102:103]
	v_mov_b32_e32 v108, v110
	v_pk_add_f32 v[104:105], v[130:131], v[102:103]
	v_cmp_neq_f32_e32 vcc, s33, v132
	v_pk_mul_f32 v[114:115], v[124:125], v[104:105]
	s_nop 0
	v_pk_mul_f32 v[120:121], v[122:123], v[114:115]
	v_pk_add_f32 v[126:127], v[116:117], v[114:115]
	v_pk_fma_f32 v[122:123], v[114:115], v[122:123], v[120:121] neg_lo:[0,0,1] neg_hi:[0,0,1]
	v_pk_add_f32 v[116:117], v[126:127], v[116:117] neg_lo:[0,1] neg_hi:[0,1]
	s_nop 0
	v_pk_add_f32 v[116:117], v[114:115], v[116:117] neg_lo:[0,1] neg_hi:[0,1]
	v_pk_fma_f32 v[114:115], v[114:115], v[118:119], v[122:123]
	s_nop 0
	v_pk_add_f32 v[118:119], v[120:121], v[114:115]
	s_nop 0
	v_pk_add_f32 v[122:123], v[104:105], v[118:119] neg_lo:[0,1] neg_hi:[0,1]
	v_pk_add_f32 v[120:121], v[118:119], v[120:121] neg_lo:[0,1] neg_hi:[0,1]
	s_nop 0
	v_pk_add_f32 v[114:115], v[120:121], v[114:115] neg_lo:[0,1] neg_hi:[0,1]
	v_pk_add_f32 v[120:121], v[130:131], v[104:105] neg_lo:[0,1] neg_hi:[0,1]
	v_pk_add_f32 v[104:105], v[104:105], v[122:123] neg_lo:[0,1] neg_hi:[0,1]
	v_pk_add_f32 v[102:103], v[102:103], v[120:121]
	v_pk_add_f32 v[104:105], v[104:105], v[118:119] neg_lo:[0,1] neg_hi:[0,1]
	v_mov_b32_e32 v121, v111
	v_pk_add_f32 v[102:103], v[102:103], v[104:105]
	s_nop 0
	v_pk_add_f32 v[102:103], v[114:115], v[102:103]
	s_nop 0
	v_pk_add_f32 v[102:103], v[122:123], v[102:103]
	s_nop 0
	v_pk_mul_f32 v[102:103], v[124:125], v[102:103]
	s_nop 0
	v_pk_add_f32 v[102:103], v[116:117], v[102:103]
	s_nop 0
	v_pk_add_f32 v[104:105], v[126:127], v[102:103]
	s_nop 0
	v_pk_add_f32 v[116:117], v[104:105], v[126:127] neg_lo:[0,1] neg_hi:[0,1]
	v_ldexp_f32 v114, v104, 1
	v_pk_add_f32 v[102:103], v[102:103], v[116:117] neg_lo:[0,1] neg_hi:[0,1]
	v_pk_mul_f32 v[116:117], v[104:105], v[104:105]
	v_ldexp_f32 v115, v105, 1
	v_pk_fma_f32 v[118:119], v[116:117], s[18:19], v[84:85] op_sel_hi:[1,0,0]
	v_pk_mul_f32 v[104:105], v[104:105], v[116:117]
	v_pk_fma_f32 v[116:117], v[116:117], v[118:119], s[20:21] op_sel_hi:[1,1,0]
	v_ldexp_f32 v102, v102, 1
	v_pk_mul_f32 v[104:105], v[104:105], v[116:117]
; __device__ __forceinline__ void p1_side_task(int c, LAS unsigned char* lds, const bf16_t* XN, const bf16_t* WIN, const float* b_f, float* LF, bf16_t* Kb, bf16_t* Vb, bf16_t* P1b) {
;     ...
;             for (int j = 0; j < 4; ++j) { const float xx = acc[g][j] + bfh; const float v = (fminf(xx, 0.f) - log1pf(__expf(-fabsf(xx)))) * LOG2E; const int m = 4 * fq + j;
;                 if (g < 2) { const int row = 32 * c + 16 * g + m; LF[(size_t)((row >> 12) * NH + fr) * KVROWS + 64 + (row & 4095)] = v; }
	v_ldexp_f32 v103, v103, 1
	v_pk_add_f32 v[116:117], v[114:115], v[104:105]
	s_nop 0
	v_pk_add_f32 v[114:115], v[116:117], v[114:115] neg_lo:[0,1] neg_hi:[0,1]
	s_nop 0
	v_pk_add_f32 v[104:105], v[104:105], v[114:115] neg_lo:[0,1] neg_hi:[0,1]
	s_nop 0
	v_pk_add_f32 v[102:103], v[102:103], v[104:105]
	s_nop 0
	v_pk_add_f32 v[104:105], v[116:117], v[102:103]
	s_nop 0
	v_pk_add_f32 v[118:119], v[110:111], v[104:105]
	v_pk_add_f32 v[114:115], v[104:105], v[116:117] neg_lo:[0,1] neg_hi:[0,1]
	v_mov_b32_e32 v120, v118
	v_pk_add_f32 v[108:109], v[120:121], v[108:109] neg_lo:[0,1] neg_hi:[0,1]
	v_mov_b32_e32 v120, v104
	v_mov_b32_e32 v121, v107
	v_pk_add_f32 v[120:121], v[120:121], v[108:109] neg_lo:[0,1] neg_hi:[0,1]
	v_mov_b32_e32 v113, v109
	v_mov_b32_e32 v104, v118
	v_mov_b32_e32 v109, v117
	v_pk_add_f32 v[108:109], v[104:105], v[108:109] neg_lo:[0,1] neg_hi:[0,1]
	v_mov_b32_e32 v116, v110
	v_mov_b32_e32 v117, v103
	v_mov_b32_e32 v115, v109
	v_pk_add_f32 v[124:125], v[118:119], v[110:111] neg_lo:[0,1] neg_hi:[0,1]
	v_pk_add_f32 v[116:117], v[116:117], v[108:109] neg_lo:[0,1] neg_hi:[0,1]
	v_pk_add_f32 v[108:109], v[102:103], v[114:115] neg_lo:[0,1] neg_hi:[0,1]
	v_mov_b32_e32 v103, v105
	v_pk_add_f32 v[104:105], v[118:119], v[124:125] neg_lo:[0,1] neg_hi:[0,1]
	v_pk_add_f32 v[122:123], v[106:107], v[112:113] neg_lo:[0,1] neg_hi:[0,1]
	v_mov_b32_e32 v115, v125
	v_mov_b32_e32 v107, v111
	v_mov_b32_e32 v113, v105
	v_pk_add_f32 v[102:103], v[102:103], v[114:115] neg_lo:[0,1] neg_hi:[0,1]
	v_pk_add_f32 v[104:105], v[106:107], v[112:113] neg_lo:[0,1] neg_hi:[0,1]
	v_pk_add_f32 v[116:117], v[120:121], v[116:117]
	v_pk_add_f32 v[102:103], v[102:103], v[104:105]
	v_mov_b32_e32 v105, v121
	v_pk_add_f32 v[106:107], v[116:117], v[102:103]
	v_mov_b32_e32 v103, v117
	v_pk_add_f32 v[104:105], v[102:103], v[104:105] neg_lo:[0,1] neg_hi:[0,1]
	v_pk_add_f32 v[110:111], v[118:119], v[106:107]
	v_pk_add_f32 v[102:103], v[102:103], v[104:105] neg_lo:[0,1] neg_hi:[0,1]
	v_pk_add_f32 v[108:109], v[108:109], v[104:105] neg_lo:[0,1] neg_hi:[0,1]
	v_pk_add_f32 v[102:103], v[122:123], v[102:103] neg_lo:[0,1] neg_hi:[0,1]
	v_pk_add_f32 v[104:105], v[110:111], v[118:119] neg_lo:[0,1] neg_hi:[0,1]
	v_pk_add_f32 v[102:103], v[108:109], v[102:103]
	v_pk_add_f32 v[104:105], v[106:107], v[104:105] neg_lo:[0,1] neg_hi:[0,1]
	s_nop 0
	v_pk_add_f32 v[102:103], v[102:103], v[104:105]
	s_nop 0
	v_pk_add_f32 v[102:103], v[110:111], v[102:103]
	s_nop 0
	v_cndmask_b32_e32 v64, v94, v102, vcc
	v_cmp_neq_f32_e32 vcc, s33, v133
	s_nop 1
	v_cndmask_b32_e32 v102, v94, v103, vcc
	v_cmp_ngt_f32_e32 vcc, -1.0, v133
	s_nop 1
	v_cndmask_b32_e32 v102, v95, v102, vcc
	v_cmp_ngt_f32_e32 vcc, -1.0, v132
	s_nop 1
	v_cndmask_b32_e32 v64, v95, v64, vcc
	v_cmp_neq_f32_e32 vcc, -1.0, v132
	s_nop 1
	v_cndmask_b32_e32 v64, v96, v64, vcc
	v_cmp_neq_f32_e32 vcc, -1.0, v133
	s_nop 1
	v_cndmask_b32_e32 v102, v96, v102, vcc
	v_cmp_lt_f32_e64 vcc, |v133|, s23
	s_nop 1
	v_cndmask_b32_e32 v103, v102, v133, vcc
	v_cmp_lt_f32_e64 vcc, |v132|, s23
	s_nop 1
	v_cndmask_b32_e32 v102, v64, v132, vcc
	v_add_f32_e32 v64, v88, v97
	v_mul_f32_e64 v88, |v64|, s19
	v_exp_f32_e32 v128, v88
	v_pk_add_f32 v[100:101], v[100:101], v[102:103] neg_lo:[0,1] neg_hi:[0,1]
	v_mul_f32_e64 v102, |v89|, s19
	v_pk_mul_f32 v[100:101], v[100:101], s[22:23] op_sel_hi:[1,0]
	v_min_f32_e32 v88, 0, v64
	v_add_f32_e32 v64, 1.0, v128
	v_exp_f32_e32 v129, v102
	global_store_dwordx4 v[86:87], v[98:101], off offset:256
	v_min_f32_e32 v89, 0, v89
	v_add_f32_e32 v104, 1.0, v129
	v_cvt_f64_f32_e32 v[98:99], v64
	v_frexp_exp_i32_f64_e32 v100, v[98:99]
	v_add_f32_e32 v98, -1.0, v64
	v_sub_f32_e32 v99, v128, v98
	v_sub_f32_e32 v98, v98, v64
	v_add_f32_e32 v98, 1.0, v98
	v_add_f32_e32 v102, v99, v98
	v_cvt_f64_f32_e32 v[98:99], v104
	v_frexp_exp_i32_f64_e32 v98, v[98:99]
	v_frexp_mant_f32_e32 v99, v104
	v_cmp_gt_f32_e32 vcc, s21, v99
	v_frexp_mant_f32_e32 v101, v64
	v_add_f32_e32 v103, -1.0, v104
	v_subbrev_co_u32_e32 v99, vcc, 0, v98, vcc
	v_cmp_gt_f32_e32 vcc, s21, v101
	v_sub_f32_e32 v105, v129, v103
	v_sub_f32_e32 v103, v103, v104
	v_subbrev_co_u32_e32 v101, vcc, 0, v100, vcc
	v_sub_u32_e32 v100, 0, v101
	v_add_f32_e32 v103, 1.0, v103
	v_ldexp_f32 v98, v64, v100
	v_sub_u32_e32 v64, 0, v99
	v_add_f32_e32 v105, v105, v103
	v_cvt_f32_i32_e32 v103, v99
	v_ldexp_f32 v99, v104, v64
	v_pk_add_f32 v[114:115], v[98:99], 1.0 op_sel_hi:[1,0]
	v_ldexp_f32 v100, v102, v100
	v_pk_add_f32 v[116:117], v[114:115], -1.0 op_sel_hi:[1,0]
	v_cvt_f32_i32_e32 v102, v101
	v_ldexp_f32 v101, v105, v64
	v_pk_add_f32 v[116:117], v[98:99], v[116:117] neg_lo:[0,1] neg_hi:[0,1]
	v_pk_add_f32 v[110:111], v[98:99], -1.0 op_sel_hi:[1,0]
	v_pk_add_f32 v[116:117], v[100:101], v[116:117]
	v_pk_add_f32 v[112:113], v[110:111], 1.0 op_sel_hi:[1,0]
	v_pk_add_f32 v[118:119], v[114:115], v[116:117]
	v_pk_add_f32 v[98:99], v[98:99], v[112:113] neg_lo:[0,1] neg_hi:[0,1]
	v_rcp_f32_e32 v120, v118
	v_rcp_f32_e32 v121, v119
	v_pk_add_f32 v[98:99], v[100:101], v[98:99]
	v_pk_add_f32 v[114:115], v[118:119], v[114:115] neg_lo:[0,1] neg_hi:[0,1]
	v_pk_add_f32 v[100:101], v[110:111], v[98:99]
	v_pk_add_f32 v[114:115], v[116:117], v[114:115] neg_lo:[0,1] neg_hi:[0,1]
	v_pk_mul_f32 v[112:113], v[100:101], v[120:121]
	v_pk_add_f32 v[110:111], v[100:101], v[110:111] neg_lo:[0,1] neg_hi:[0,1]
	v_pk_mul_f32 v[122:123], v[118:119], v[112:113]
	v_pk_add_f32 v[98:99], v[98:99], v[110:111] neg_lo:[0,1] neg_hi:[0,1]
	v_pk_fma_f32 v[116:117], v[112:113], v[118:119], v[122:123] neg_lo:[0,0,1] neg_hi:[0,0,1]
	v_pk_mul_f32 v[104:105], v[102:103], s[12:13] op_sel_hi:[1,0]
	v_pk_fma_f32 v[116:117], v[112:113], v[114:115], v[116:117]
; __device__ __forceinline__ void p1_side_task(int c, LAS unsigned char* lds, const bf16_t* XN, const bf16_t* WIN, const float* b_f, float* LF, bf16_t* Kb, bf16_t* Vb, bf16_t* P1b) {
;     ...
;             for (int j = 0; j < 4; ++j) { const float xx = acc[g][j] + bfh; const float v = (fminf(xx, 0.f) - log1pf(__expf(-fabsf(xx)))) * LOG2E; const int m = 4 * fq + j;
;                 if (g < 2) { const int row = 32 * c + 16 * g + m; LF[(size_t)((row >> 12) * NH + fr) * KVROWS + 64 + (row & 4095)] = v; }
	v_pk_fma_f32 v[106:107], v[102:103], s[12:13], v[104:105] op_sel_hi:[1,0,1] neg_lo:[0,0,1] neg_hi:[0,0,1]
	v_pk_add_f32 v[124:125], v[122:123], v[116:117]
	v_pk_fma_f32 v[102:103], v[102:103], s[14:15], v[106:107] op_sel_hi:[1,0,1]
	v_pk_add_f32 v[126:127], v[100:101], v[124:125] neg_lo:[0,1] neg_hi:[0,1]
	v_pk_add_f32 v[122:123], v[124:125], v[122:123] neg_lo:[0,1] neg_hi:[0,1]
	v_pk_add_f32 v[100:101], v[100:101], v[126:127] neg_lo:[0,1] neg_hi:[0,1]
	v_pk_add_f32 v[116:117], v[122:123], v[116:117] neg_lo:[0,1] neg_hi:[0,1]
	v_pk_add_f32 v[100:101], v[100:101], v[124:125] neg_lo:[0,1] neg_hi:[0,1]
	v_pk_add_f32 v[106:107], v[104:105], v[102:103]
	v_pk_add_f32 v[98:99], v[98:99], v[100:101]
	v_pk_add_f32 v[108:109], v[106:107], v[104:105] neg_lo:[0,1] neg_hi:[0,1]
	v_pk_add_f32 v[98:99], v[116:117], v[98:99]
	v_mov_b32_e32 v104, v106
	v_pk_add_f32 v[100:101], v[126:127], v[98:99]
	v_cmp_neq_f32_e32 vcc, s33, v128
	v_pk_mul_f32 v[110:111], v[120:121], v[100:101]
	s_nop 0
	v_pk_mul_f32 v[116:117], v[118:119], v[110:111]
	v_pk_add_f32 v[122:123], v[112:113], v[110:111]
	v_pk_fma_f32 v[118:119], v[110:111], v[118:119], v[116:117] neg_lo:[0,0,1] neg_hi:[0,0,1]
	v_pk_add_f32 v[112:113], v[122:123], v[112:113] neg_lo:[0,1] neg_hi:[0,1]
	s_nop 0
	v_pk_add_f32 v[112:113], v[110:111], v[112:113] neg_lo:[0,1] neg_hi:[0,1]
	v_pk_fma_f32 v[110:111], v[110:111], v[114:115], v[118:119]
	s_nop 0
	v_pk_add_f32 v[114:115], v[116:117], v[110:111]
	s_nop 0
	v_pk_add_f32 v[118:119], v[100:101], v[114:115] neg_lo:[0,1] neg_hi:[0,1]
	v_pk_add_f32 v[116:117], v[114:115], v[116:117] neg_lo:[0,1] neg_hi:[0,1]
	s_nop 0
	v_pk_add_f32 v[110:111], v[116:117], v[110:111] neg_lo:[0,1] neg_hi:[0,1]
	v_pk_add_f32 v[116:117], v[126:127], v[100:101] neg_lo:[0,1] neg_hi:[0,1]
	v_pk_add_f32 v[100:101], v[100:101], v[118:119] neg_lo:[0,1] neg_hi:[0,1]
	v_pk_add_f32 v[98:99], v[98:99], v[116:117]
	v_pk_add_f32 v[100:101], v[100:101], v[114:115] neg_lo:[0,1] neg_hi:[0,1]
	v_mov_b32_e32 v117, v107
	v_pk_add_f32 v[98:99], v[98:99], v[100:101]
	s_nop 0
	v_pk_add_f32 v[98:99], v[110:111], v[98:99]
	s_nop 0
	v_pk_add_f32 v[98:99], v[118:119], v[98:99]
	s_nop 0
	v_pk_mul_f32 v[98:99], v[120:121], v[98:99]
	s_nop 0
	v_pk_add_f32 v[98:99], v[112:113], v[98:99]
	s_nop 0
	v_pk_add_f32 v[100:101], v[122:123], v[98:99]
	s_nop 0
	v_pk_add_f32 v[112:113], v[100:101], v[122:123] neg_lo:[0,1] neg_hi:[0,1]
	v_ldexp_f32 v110, v100, 1
	v_pk_add_f32 v[98:99], v[98:99], v[112:113] neg_lo:[0,1] neg_hi:[0,1]
	v_pk_mul_f32 v[112:113], v[100:101], v[100:101]
	v_ldexp_f32 v111, v101, 1
	v_pk_fma_f32 v[114:115], v[112:113], s[18:19], v[84:85] op_sel_hi:[1,0,0]
	v_pk_mul_f32 v[100:101], v[100:101], v[112:113]
	v_pk_fma_f32 v[112:113], v[112:113], v[114:115], s[20:21] op_sel_hi:[1,1,0]
	v_ldexp_f32 v98, v98, 1
	v_pk_mul_f32 v[100:101], v[100:101], v[112:113]
	v_ldexp_f32 v99, v99, 1
	v_pk_add_f32 v[112:113], v[110:111], v[100:101]
	s_nop 0
	v_pk_add_f32 v[110:111], v[112:113], v[110:111] neg_lo:[0,1] neg_hi:[0,1]
	s_nop 0
	v_pk_add_f32 v[100:101], v[100:101], v[110:111] neg_lo:[0,1] neg_hi:[0,1]
	s_nop 0
	v_pk_add_f32 v[98:99], v[98:99], v[100:101]
	s_nop 0
	v_pk_add_f32 v[100:101], v[112:113], v[98:99]
	s_nop 0
	v_pk_add_f32 v[114:115], v[106:107], v[100:101]
	v_pk_add_f32 v[110:111], v[100:101], v[112:113] neg_lo:[0,1] neg_hi:[0,1]
	v_mov_b32_e32 v116, v114
	v_pk_add_f32 v[104:105], v[116:117], v[104:105] neg_lo:[0,1] neg_hi:[0,1]
	v_mov_b32_e32 v116, v100
	v_mov_b32_e32 v117, v103
	v_pk_add_f32 v[116:117], v[116:117], v[104:105] neg_lo:[0,1] neg_hi:[0,1]
	v_mov_b32_e32 v109, v105
	v_mov_b32_e32 v100, v114
	v_mov_b32_e32 v105, v113
	v_pk_add_f32 v[104:105], v[100:101], v[104:105] neg_lo:[0,1] neg_hi:[0,1]
	v_mov_b32_e32 v112, v106
	v_mov_b32_e32 v113, v99
	v_mov_b32_e32 v111, v105
	v_pk_add_f32 v[120:121], v[114:115], v[106:107] neg_lo:[0,1] neg_hi:[0,1]
	v_pk_add_f32 v[112:113], v[112:113], v[104:105] neg_lo:[0,1] neg_hi:[0,1]
	v_pk_add_f32 v[104:105], v[98:99], v[110:111] neg_lo:[0,1] neg_hi:[0,1]
	v_mov_b32_e32 v99, v101
	v_pk_add_f32 v[100:101], v[114:115], v[120:121] neg_lo:[0,1] neg_hi:[0,1]
	v_pk_add_f32 v[118:119], v[102:103], v[108:109] neg_lo:[0,1] neg_hi:[0,1]
	v_mov_b32_e32 v111, v121
	v_mov_b32_e32 v103, v107
	v_mov_b32_e32 v109, v101
	v_pk_add_f32 v[98:99], v[98:99], v[110:111] neg_lo:[0,1] neg_hi:[0,1]
	v_pk_add_f32 v[100:101], v[102:103], v[108:109] neg_lo:[0,1] neg_hi:[0,1]
	v_pk_add_f32 v[112:113], v[116:117], v[112:113]
	v_pk_add_f32 v[98:99], v[98:99], v[100:101]
	v_mov_b32_e32 v101, v117
	v_pk_add_f32 v[102:103], v[112:113], v[98:99]
	v_mov_b32_e32 v99, v113
	v_pk_add_f32 v[100:101], v[98:99], v[100:101] neg_lo:[0,1] neg_hi:[0,1]
	v_pk_add_f32 v[106:107], v[114:115], v[102:103]
	v_pk_add_f32 v[98:99], v[98:99], v[100:101] neg_lo:[0,1] neg_hi:[0,1]
	v_pk_add_f32 v[104:105], v[104:105], v[100:101] neg_lo:[0,1] neg_hi:[0,1]
	v_pk_add_f32 v[98:99], v[118:119], v[98:99] neg_lo:[0,1] neg_hi:[0,1]
	v_pk_add_f32 v[100:101], v[106:107], v[114:115] neg_lo:[0,1] neg_hi:[0,1]
	v_pk_add_f32 v[98:99], v[104:105], v[98:99]
	v_pk_add_f32 v[100:101], v[102:103], v[100:101] neg_lo:[0,1] neg_hi:[0,1]
	v_mul_f32_e64 v102, |v83|, s19
	v_pk_add_f32 v[98:99], v[98:99], v[100:101]
	v_min_f32_e32 v83, 0, v83
	v_pk_add_f32 v[98:99], v[106:107], v[98:99]
	s_nop 0
	v_cndmask_b32_e32 v64, v94, v98, vcc
	v_cmp_neq_f32_e32 vcc, s33, v129
	s_nop 1
	v_cndmask_b32_e32 v98, v94, v99, vcc
	v_cmp_ngt_f32_e32 vcc, -1.0, v129
	s_nop 1
	v_cndmask_b32_e32 v98, v95, v98, vcc
	v_cmp_ngt_f32_e32 vcc, -1.0, v128
	s_nop 1
	v_cndmask_b32_e32 v64, v95, v64, vcc
	v_cmp_neq_f32_e32 vcc, -1.0, v128
	s_nop 1
	v_cndmask_b32_e32 v64, v96, v64, vcc
; __device__ __forceinline__ void p1_side_task(int c, LAS unsigned char* lds, const bf16_t* XN, const bf16_t* WIN, const float* b_f, float* LF, bf16_t* Kb, bf16_t* Vb, bf16_t* P1b) {
;     ...
;             for (int j = 0; j < 4; ++j) { const float xx = acc[g][j] + bfh; const float v = (fminf(xx, 0.f) - log1pf(__expf(-fabsf(xx)))) * LOG2E; const int m = 4 * fq + j;
;                 if (g < 2) { const int row = 32 * c + 16 * g + m; LF[(size_t)((row >> 12) * NH + fr) * KVROWS + 64 + (row & 4095)] = v; }
	v_cmp_neq_f32_e32 vcc, -1.0, v129
	s_nop 1
	v_cndmask_b32_e32 v98, v96, v98, vcc
	v_cmp_lt_f32_e64 vcc, |v129|, s23
	s_nop 1
	v_cndmask_b32_e32 v99, v98, v129, vcc
	v_cmp_lt_f32_e64 vcc, |v128|, s23
	v_exp_f32_e32 v129, v102
	s_nop 0
	v_cndmask_b32_e32 v98, v64, v128, vcc
	v_add_f32_e32 v64, v82, v97
	v_mul_f32_e64 v82, |v64|, s19
	v_exp_f32_e32 v128, v82
	v_pk_add_f32 v[88:89], v[88:89], v[98:99] neg_lo:[0,1] neg_hi:[0,1]
	v_min_f32_e32 v82, 0, v64
	v_pk_mul_f32 v[98:99], v[88:89], s[22:23] op_sel_hi:[1,0]
	v_add_f32_e32 v64, 1.0, v128
	v_cvt_f64_f32_e32 v[88:89], v64
	v_frexp_exp_i32_f64_e32 v100, v[88:89]
	v_add_f32_e32 v88, -1.0, v64
	v_sub_f32_e32 v89, v128, v88
	v_sub_f32_e32 v88, v88, v64
	v_add_f32_e32 v88, 1.0, v88
	v_add_f32_e32 v104, 1.0, v129
	v_add_f32_e32 v102, v89, v88
	v_cvt_f64_f32_e32 v[88:89], v104
	v_frexp_exp_i32_f64_e32 v88, v[88:89]
	v_frexp_mant_f32_e32 v89, v104
	v_cmp_gt_f32_e32 vcc, s21, v89
	v_frexp_mant_f32_e32 v101, v64
	v_add_f32_e32 v103, -1.0, v104
	v_subbrev_co_u32_e32 v89, vcc, 0, v88, vcc
	v_cmp_gt_f32_e32 vcc, s21, v101
	v_sub_f32_e32 v105, v129, v103
	v_sub_f32_e32 v103, v103, v104
	v_subbrev_co_u32_e32 v101, vcc, 0, v100, vcc
	v_sub_u32_e32 v100, 0, v101
	v_add_f32_e32 v103, 1.0, v103
	v_ldexp_f32 v88, v64, v100
	v_sub_u32_e32 v64, 0, v89
	v_add_f32_e32 v105, v105, v103
	v_cvt_f32_i32_e32 v103, v89
	v_ldexp_f32 v89, v104, v64
	v_pk_add_f32 v[114:115], v[88:89], 1.0 op_sel_hi:[1,0]
	v_ldexp_f32 v100, v102, v100
	v_pk_add_f32 v[116:117], v[114:115], -1.0 op_sel_hi:[1,0]
	v_cvt_f32_i32_e32 v102, v101
	v_ldexp_f32 v101, v105, v64
	v_pk_add_f32 v[116:117], v[88:89], v[116:117] neg_lo:[0,1] neg_hi:[0,1]
	v_pk_add_f32 v[110:111], v[88:89], -1.0 op_sel_hi:[1,0]
	v_pk_add_f32 v[116:117], v[100:101], v[116:117]
	v_pk_add_f32 v[112:113], v[110:111], 1.0 op_sel_hi:[1,0]
	v_pk_add_f32 v[118:119], v[114:115], v[116:117]
	v_pk_add_f32 v[88:89], v[88:89], v[112:113] neg_lo:[0,1] neg_hi:[0,1]
	v_rcp_f32_e32 v120, v118
	v_rcp_f32_e32 v121, v119
	v_pk_add_f32 v[88:89], v[100:101], v[88:89]
	v_pk_add_f32 v[114:115], v[118:119], v[114:115] neg_lo:[0,1] neg_hi:[0,1]
	v_pk_add_f32 v[100:101], v[110:111], v[88:89]
	v_pk_add_f32 v[114:115], v[116:117], v[114:115] neg_lo:[0,1] neg_hi:[0,1]
	v_pk_mul_f32 v[112:113], v[100:101], v[120:121]
	v_pk_add_f32 v[110:111], v[100:101], v[110:111] neg_lo:[0,1] neg_hi:[0,1]
	v_pk_mul_f32 v[122:123], v[118:119], v[112:113]
	v_pk_add_f32 v[88:89], v[88:89], v[110:111] neg_lo:[0,1] neg_hi:[0,1]
	v_pk_fma_f32 v[116:117], v[112:113], v[118:119], v[122:123] neg_lo:[0,0,1] neg_hi:[0,0,1]
	v_pk_mul_f32 v[104:105], v[102:103], s[12:13] op_sel_hi:[1,0]
	v_pk_fma_f32 v[116:117], v[112:113], v[114:115], v[116:117]
	v_pk_fma_f32 v[106:107], v[102:103], s[12:13], v[104:105] op_sel_hi:[1,0,1] neg_lo:[0,0,1] neg_hi:[0,0,1]
	v_pk_add_f32 v[124:125], v[122:123], v[116:117]
	v_pk_fma_f32 v[102:103], v[102:103], s[14:15], v[106:107] op_sel_hi:[1,0,1]
	v_pk_add_f32 v[126:127], v[100:101], v[124:125] neg_lo:[0,1] neg_hi:[0,1]
	v_pk_add_f32 v[122:123], v[124:125], v[122:123] neg_lo:[0,1] neg_hi:[0,1]
	v_pk_add_f32 v[100:101], v[100:101], v[126:127] neg_lo:[0,1] neg_hi:[0,1]
	v_pk_add_f32 v[116:117], v[122:123], v[116:117] neg_lo:[0,1] neg_hi:[0,1]
	v_pk_add_f32 v[100:101], v[100:101], v[124:125] neg_lo:[0,1] neg_hi:[0,1]
	v_pk_add_f32 v[106:107], v[104:105], v[102:103]
	v_pk_add_f32 v[88:89], v[88:89], v[100:101]
	v_pk_add_f32 v[108:109], v[106:107], v[104:105] neg_lo:[0,1] neg_hi:[0,1]
	v_pk_add_f32 v[88:89], v[116:117], v[88:89]
	v_mov_b32_e32 v104, v106
	v_pk_add_f32 v[100:101], v[126:127], v[88:89]
	v_cmp_neq_f32_e32 vcc, s33, v128
	v_pk_mul_f32 v[110:111], v[120:121], v[100:101]
	s_nop 0
	v_pk_mul_f32 v[116:117], v[118:119], v[110:111]
	v_pk_add_f32 v[122:123], v[112:113], v[110:111]
	v_pk_fma_f32 v[118:119], v[110:111], v[118:119], v[116:117] neg_lo:[0,0,1] neg_hi:[0,0,1]
	v_pk_add_f32 v[112:113], v[122:123], v[112:113] neg_lo:[0,1] neg_hi:[0,1]
	s_nop 0
	v_pk_add_f32 v[112:113], v[110:111], v[112:113] neg_lo:[0,1] neg_hi:[0,1]
	v_pk_fma_f32 v[110:111], v[110:111], v[114:115], v[118:119]
	s_nop 0
	v_pk_add_f32 v[114:115], v[116:117], v[110:111]
	s_nop 0
	v_pk_add_f32 v[118:119], v[100:101], v[114:115] neg_lo:[0,1] neg_hi:[0,1]
	v_pk_add_f32 v[116:117], v[114:115], v[116:117] neg_lo:[0,1] neg_hi:[0,1]
	s_nop 0
	v_pk_add_f32 v[110:111], v[116:117], v[110:111] neg_lo:[0,1] neg_hi:[0,1]
	v_pk_add_f32 v[116:117], v[126:127], v[100:101] neg_lo:[0,1] neg_hi:[0,1]
	v_pk_add_f32 v[100:101], v[100:101], v[118:119] neg_lo:[0,1] neg_hi:[0,1]
	v_pk_add_f32 v[88:89], v[88:89], v[116:117]
	v_pk_add_f32 v[100:101], v[100:101], v[114:115] neg_lo:[0,1] neg_hi:[0,1]
	v_mov_b32_e32 v115, v107
	v_pk_add_f32 v[88:89], v[88:89], v[100:101]
	s_nop 0
	v_pk_add_f32 v[88:89], v[110:111], v[88:89]
	s_nop 0
	v_pk_add_f32 v[88:89], v[118:119], v[88:89]
	s_nop 0
	v_pk_mul_f32 v[88:89], v[120:121], v[88:89]
	s_nop 0
	v_pk_add_f32 v[88:89], v[112:113], v[88:89]
	s_nop 0
	v_pk_add_f32 v[100:101], v[122:123], v[88:89]
	s_nop 0
	v_pk_add_f32 v[112:113], v[100:101], v[122:123] neg_lo:[0,1] neg_hi:[0,1]
	v_ldexp_f32 v110, v100, 1
	v_pk_add_f32 v[88:89], v[88:89], v[112:113] neg_lo:[0,1] neg_hi:[0,1]
	v_pk_mul_f32 v[112:113], v[100:101], v[100:101]
	v_ldexp_f32 v111, v101, 1
	v_pk_fma_f32 v[84:85], v[112:113], s[18:19], v[84:85] op_sel_hi:[1,0,0]
	v_pk_mul_f32 v[100:101], v[100:101], v[112:113]
	v_pk_fma_f32 v[84:85], v[112:113], v[84:85], s[20:21] op_sel_hi:[1,1,0]
	v_ldexp_f32 v88, v88, 1
	v_pk_mul_f32 v[84:85], v[100:101], v[84:85]
	v_ldexp_f32 v89, v89, 1
	v_pk_add_f32 v[100:101], v[110:111], v[84:85]
	s_nop 0
; __device__ __forceinline__ void p1_side_task(int c, LAS unsigned char* lds, const bf16_t* XN, const bf16_t* WIN, const float* b_f, float* LF, bf16_t* Kb, bf16_t* Vb, bf16_t* P1b) {
;     ...
;         const float bfh = b_f[fr];
; #pragma unroll
;         for (int g = 0; g < 3; ++g)
; #pragma unroll
;             for (int j = 0; j < 4; ++j) { const float xx = acc[g][j] + bfh; const float v = (fminf(xx, 0.f) - log1pf(__expf(-fabsf(xx)))) * LOG2E; const int m = 4 * fq + j;
;                 if (g < 2) { const int row = 32 * c + 16 * g + m; LF[(size_t)((row >> 12) * NH + fr) * KVROWS + 64 + (row & 4095)] = v; }
;                 else if (c == 0) { LF[(size_t)fr * KVROWS + 48 + m] = v; LF[(size_t)(NH + fr) * KVROWS + 48 + m] = v; } }
	v_pk_add_f32 v[110:111], v[100:101], v[110:111] neg_lo:[0,1] neg_hi:[0,1]
	s_nop 0
	v_pk_add_f32 v[84:85], v[84:85], v[110:111] neg_lo:[0,1] neg_hi:[0,1]
	s_nop 0
	v_pk_add_f32 v[84:85], v[88:89], v[84:85]
	s_nop 0
	v_pk_add_f32 v[88:89], v[100:101], v[84:85]
	s_nop 0
	v_pk_add_f32 v[112:113], v[106:107], v[88:89]
	v_pk_add_f32 v[110:111], v[88:89], v[100:101] neg_lo:[0,1] neg_hi:[0,1]
	v_mov_b32_e32 v114, v112
	v_pk_add_f32 v[104:105], v[114:115], v[104:105] neg_lo:[0,1] neg_hi:[0,1]
	v_mov_b32_e32 v114, v88
	v_mov_b32_e32 v115, v103
	v_pk_add_f32 v[114:115], v[114:115], v[104:105] neg_lo:[0,1] neg_hi:[0,1]
	v_mov_b32_e32 v109, v105
	v_mov_b32_e32 v88, v112
	v_mov_b32_e32 v105, v101
	v_pk_add_f32 v[100:101], v[88:89], v[104:105] neg_lo:[0,1] neg_hi:[0,1]
	v_mov_b32_e32 v104, v106
	v_mov_b32_e32 v105, v85
	v_mov_b32_e32 v111, v101
	v_pk_add_f32 v[118:119], v[112:113], v[106:107] neg_lo:[0,1] neg_hi:[0,1]
	v_pk_add_f32 v[104:105], v[104:105], v[100:101] neg_lo:[0,1] neg_hi:[0,1]
	v_pk_add_f32 v[100:101], v[84:85], v[110:111] neg_lo:[0,1] neg_hi:[0,1]
	v_mov_b32_e32 v85, v89
	v_pk_add_f32 v[88:89], v[112:113], v[118:119] neg_lo:[0,1] neg_hi:[0,1]
	v_pk_add_f32 v[116:117], v[102:103], v[108:109] neg_lo:[0,1] neg_hi:[0,1]
	v_mov_b32_e32 v111, v119
	v_mov_b32_e32 v103, v107
	v_mov_b32_e32 v109, v89
	v_pk_add_f32 v[84:85], v[84:85], v[110:111] neg_lo:[0,1] neg_hi:[0,1]
	v_pk_add_f32 v[88:89], v[102:103], v[108:109] neg_lo:[0,1] neg_hi:[0,1]
	v_pk_add_f32 v[104:105], v[114:115], v[104:105]
	v_pk_add_f32 v[84:85], v[84:85], v[88:89]
	v_mov_b32_e32 v89, v115
	v_pk_add_f32 v[102:103], v[104:105], v[84:85]
	v_mov_b32_e32 v85, v105
	v_pk_add_f32 v[88:89], v[84:85], v[88:89] neg_lo:[0,1] neg_hi:[0,1]
	v_pk_add_f32 v[106:107], v[112:113], v[102:103]
	v_pk_add_f32 v[84:85], v[84:85], v[88:89] neg_lo:[0,1] neg_hi:[0,1]
	v_pk_add_f32 v[100:101], v[100:101], v[88:89] neg_lo:[0,1] neg_hi:[0,1]
	v_pk_add_f32 v[84:85], v[116:117], v[84:85] neg_lo:[0,1] neg_hi:[0,1]
	v_pk_add_f32 v[88:89], v[106:107], v[112:113] neg_lo:[0,1] neg_hi:[0,1]
	v_pk_add_f32 v[84:85], v[100:101], v[84:85]
	v_pk_add_f32 v[88:89], v[102:103], v[88:89] neg_lo:[0,1] neg_hi:[0,1]
	s_nop 0
	v_pk_add_f32 v[84:85], v[84:85], v[88:89]
	s_nop 0
	v_pk_add_f32 v[84:85], v[106:107], v[84:85]
	s_nop 0
	v_cndmask_b32_e32 v64, v94, v84, vcc
	v_cmp_neq_f32_e32 vcc, s33, v129
	s_nop 1
	v_cndmask_b32_e32 v84, v94, v85, vcc
	v_cmp_ngt_f32_e32 vcc, -1.0, v129
	s_nop 1
	v_cndmask_b32_e32 v84, v95, v84, vcc
	v_cmp_ngt_f32_e32 vcc, -1.0, v128
	s_nop 1
	v_cndmask_b32_e32 v64, v95, v64, vcc
	v_cmp_neq_f32_e32 vcc, -1.0, v128
	s_nop 1
	v_cndmask_b32_e32 v64, v96, v64, vcc
	v_cmp_neq_f32_e32 vcc, -1.0, v129
	s_nop 1
	v_cndmask_b32_e32 v84, v96, v84, vcc
	v_cmp_lt_f32_e64 vcc, |v129|, s23
	s_nop 1
	v_cndmask_b32_e32 v85, v84, v129, vcc
	v_cmp_lt_f32_e64 vcc, |v128|, s23
	s_nop 1
	v_cndmask_b32_e32 v84, v64, v128, vcc
	v_pk_add_f32 v[82:83], v[82:83], v[84:85] neg_lo:[0,1] neg_hi:[0,1]
	s_nop 0
	v_pk_mul_f32 v[100:101], v[82:83], s[22:23] op_sel_hi:[1,0]
	global_store_dwordx4 v[86:87], v[98:101], off offset:320
	s_cbranch_scc1 .LBB0_426
	ds_read_b128 v[82:85], v91 offset:2048
	ds_read_b128 v[86:89], v91 offset:7168
	ds_read_b128 v[98:101], v91 offset:12288
	ds_read_b128 v[102:105], v91 offset:17408
	ds_read_b128 v[106:109], v91 offset:22528
	ds_read_b128 v[110:113], v91 offset:27648
	ds_read_b128 v[114:117], v91 offset:32768
	ds_read_b128 v[118:121], v91 offset:37888
	s_waitcnt lgkmcnt(6)
	v_pk_add_f32 v[82:83], v[82:83], v[86:87]
	v_pk_add_f32 v[84:85], v[84:85], v[88:89]
	s_waitcnt lgkmcnt(5)
	v_pk_add_f32 v[82:83], v[82:83], v[98:99]
	v_pk_add_f32 v[84:85], v[84:85], v[100:101]
	s_waitcnt lgkmcnt(4)
	v_pk_add_f32 v[82:83], v[82:83], v[102:103]
	s_waitcnt lgkmcnt(3)
	v_pk_add_f32 v[82:83], v[82:83], v[106:107]
	s_waitcnt lgkmcnt(2)
	v_pk_add_f32 v[82:83], v[82:83], v[110:111]
	s_waitcnt lgkmcnt(1)
	v_pk_add_f32 v[82:83], v[82:83], v[114:115]
	s_waitcnt lgkmcnt(0)
	v_pk_add_f32 v[86:87], v[82:83], v[118:119]
	s_nop 0
	v_add_f32_e32 v64, v86, v97
	v_mul_f32_e64 v82, |v64|, s19
	v_exp_f32_e32 v86, v82
	v_pk_add_f32 v[82:83], v[84:85], v[104:105]
	v_add_f32_e32 v87, v87, v97
	v_min_f32_e32 v64, 0, v64
	v_add_f32_e32 v88, 1.0, v86
	v_cvt_f64_f32_e32 v[84:85], v88
	v_frexp_exp_i32_f64_e32 v84, v[84:85]
	v_frexp_mant_f32_e32 v85, v88
	v_cmp_gt_f32_e32 vcc, s21, v85
	v_add_f32_e32 v101, -1.0, v88
	v_sub_f32_e32 v102, v86, v101
	v_subbrev_co_u32_e32 v84, vcc, 0, v84, vcc
	v_cvt_f32_i32_e32 v85, v84
	v_sub_u32_e32 v84, 0, v84
	v_ldexp_f32 v99, v88, v84
	v_sub_f32_e32 v88, v101, v88
	v_add_f32_e32 v88, 1.0, v88
	v_add_f32_e32 v101, 1.0, v99
	v_add_f32_e32 v88, v102, v88
	v_add_f32_e32 v102, -1.0, v101
	v_ldexp_f32 v84, v88, v84
	v_sub_f32_e32 v102, v99, v102
	v_add_f32_e32 v102, v84, v102
	v_add_f32_e32 v100, -1.0, v99
	v_add_f32_e32 v103, v101, v102
	v_add_f32_e32 v88, 1.0, v100
	v_rcp_f32_e32 v104, v103
	v_sub_f32_e32 v88, v99, v88
	v_add_f32_e32 v84, v84, v88
	v_add_f32_e32 v88, v100, v84
	v_mul_f32_e32 v99, v88, v104
	v_mul_f32_e32 v105, v103, v99
	v_sub_f32_e32 v101, v103, v101
	v_sub_f32_e32 v101, v102, v101
	v_fma_f32 v102, v99, v103, -v105
	v_fmac_f32_e32 v102, v99, v101
	v_add_f32_e32 v106, v105, v102
	v_sub_f32_e32 v107, v88, v106
	v_sub_f32_e32 v100, v88, v100
	v_sub_f32_e32 v88, v88, v107
	v_sub_f32_e32 v105, v106, v105
	v_sub_f32_e32 v84, v84, v100
	v_sub_f32_e32 v88, v88, v106
	v_sub_f32_e32 v102, v105, v102
	v_add_f32_e32 v84, v84, v88
	v_add_f32_e32 v84, v102, v84
	v_add_f32_e32 v88, v107, v84
	v_mul_f32_e32 v100, v104, v88
	v_mul_f32_e32 v105, v103, v100
	v_add_f32_e32 v102, v99, v100
; __device__ __forceinline__ void p1_side_task(int c, LAS unsigned char* lds, const bf16_t* XN, const bf16_t* WIN, const float* b_f, float* LF, bf16_t* Kb, bf16_t* Vb, bf16_t* P1b) {
;     ...
;             for (int j = 0; j < 4; ++j) { const float xx = acc[g][j] + bfh; const float v = (fminf(xx, 0.f) - log1pf(__expf(-fabsf(xx)))) * LOG2E; const int m = 4 * fq + j;
;                 if (g < 2) { const int row = 32 * c + 16 * g + m; LF[(size_t)((row >> 12) * NH + fr) * KVROWS + 64 + (row & 4095)] = v; }
;                 else if (c == 0) { LF[(size_t)fr * KVROWS + 48 + m] = v; LF[(size_t)(NH + fr) * KVROWS + 48 + m] = v; } }
	v_fma_f32 v103, v100, v103, -v105
	v_sub_f32_e32 v99, v102, v99
	v_fmac_f32_e32 v103, v100, v101
	v_sub_f32_e32 v99, v100, v99
	v_add_f32_e32 v100, v105, v103
	v_sub_f32_e32 v101, v88, v100
	v_sub_f32_e32 v105, v100, v105
	v_sub_f32_e32 v103, v105, v103
	v_sub_f32_e32 v105, v107, v88
	v_sub_f32_e32 v88, v88, v101
	v_add_f32_e32 v84, v84, v105
	v_sub_f32_e32 v88, v88, v100
	v_add_f32_e32 v84, v84, v88
	v_add_f32_e32 v84, v103, v84
	v_add_f32_e32 v84, v101, v84
	v_mul_f32_e32 v84, v104, v84
	v_add_f32_e32 v84, v99, v84
	v_add_f32_e32 v88, v102, v84
	v_mul_f32_e32 v100, v88, v88
	v_fmamk_f32 v103, v100, 0x3e9b6dac, v93
	v_mul_f32_e32 v101, v88, v100
	v_fmaak_f32 v100, v100, v103, 0x3f2aaada
	v_ldexp_f32 v99, v88, 1
	v_mul_f32_e32 v100, v101, v100
	v_add_f32_e32 v101, v99, v100
	v_sub_f32_e32 v88, v88, v102
	v_mul_f32_e32 v89, 0x3f317218, v85
	v_sub_f32_e32 v84, v84, v88
	v_sub_f32_e32 v88, v101, v99
	v_fma_f32 v98, v85, s12, -v89
	v_ldexp_f32 v84, v84, 1
	v_sub_f32_e32 v88, v100, v88
	v_fmac_f32_e32 v98, 0xb102e308, v85
	v_add_f32_e32 v84, v84, v88
	v_add_f32_e32 v85, v89, v98
	v_add_f32_e32 v88, v101, v84
	v_add_f32_e32 v99, v85, v88
	v_sub_f32_e32 v89, v85, v89
	v_sub_f32_e32 v89, v98, v89
	v_sub_f32_e32 v98, v88, v101
	v_sub_f32_e32 v100, v99, v85
	v_sub_f32_e32 v84, v84, v98
	v_sub_f32_e32 v88, v88, v100
	v_sub_f32_e32 v100, v99, v100
	v_add_f32_e32 v98, v89, v84
	v_sub_f32_e32 v85, v85, v100
	v_add_f32_e32 v85, v88, v85
	v_sub_f32_e32 v100, v98, v89
	v_add_f32_e32 v85, v98, v85
	v_sub_f32_e32 v98, v98, v100
	v_add_f32_e32 v88, v99, v85
	v_sub_f32_e32 v84, v84, v100
	v_sub_f32_e32 v89, v89, v98
	v_add_f32_e32 v84, v84, v89
	v_sub_f32_e32 v89, v88, v99
	v_sub_f32_e32 v85, v85, v89
	v_add_f32_e32 v84, v84, v85
	v_mul_f32_e64 v85, |v87|, s19
	v_add_f32_e32 v84, v88, v84
	v_cmp_neq_f32_e32 vcc, s33, v86
	v_exp_f32_e32 v88, v85
	v_pk_add_f32 v[82:83], v[82:83], v[108:109]
	v_cndmask_b32_e32 v84, v94, v84, vcc
	v_cmp_ngt_f32_e32 vcc, -1.0, v86
	v_pk_add_f32 v[82:83], v[82:83], v[112:113]
	s_nop 0
	v_cndmask_b32_e32 v84, v95, v84, vcc
	v_cmp_neq_f32_e32 vcc, -1.0, v86
	v_pk_add_f32 v[82:83], v[82:83], v[116:117]
	s_nop 0
	v_cndmask_b32_e32 v84, v96, v84, vcc
	v_cmp_lt_f32_e64 vcc, |v86|, s23
	v_pk_add_f32 v[82:83], v[82:83], v[120:121]
	s_nop 0
	v_cndmask_b32_e32 v84, v84, v86, vcc
	v_add_f32_e32 v86, 1.0, v88
	v_sub_f32_e32 v64, v64, v84
	v_cvt_f64_f32_e32 v[84:85], v86
	v_frexp_exp_i32_f64_e32 v84, v[84:85]
	v_frexp_mant_f32_e32 v85, v86
	v_cmp_gt_f32_e32 vcc, s21, v85
	v_add_f32_e32 v100, -1.0, v86
	v_sub_f32_e32 v101, v88, v100
	v_subbrev_co_u32_e32 v84, vcc, 0, v84, vcc
	v_cvt_f32_i32_e32 v85, v84
	v_sub_u32_e32 v84, 0, v84
	v_ldexp_f32 v98, v86, v84
	v_sub_f32_e32 v86, v100, v86
	v_add_f32_e32 v86, 1.0, v86
	v_add_f32_e32 v100, 1.0, v98
	v_add_f32_e32 v86, v101, v86
	v_add_f32_e32 v101, -1.0, v100
	v_ldexp_f32 v84, v86, v84
	v_sub_f32_e32 v101, v98, v101
	v_add_f32_e32 v101, v84, v101
	v_add_f32_e32 v99, -1.0, v98
	v_add_f32_e32 v102, v100, v101
	v_add_f32_e32 v86, 1.0, v99
	v_rcp_f32_e32 v103, v102
	v_sub_f32_e32 v86, v98, v86
	v_add_f32_e32 v84, v84, v86
	v_add_f32_e32 v86, v99, v84
	v_mul_f32_e32 v98, v86, v103
	v_mul_f32_e32 v104, v102, v98
	v_sub_f32_e32 v100, v102, v100
	v_sub_f32_e32 v100, v101, v100
	v_fma_f32 v101, v98, v102, -v104
	v_fmac_f32_e32 v101, v98, v100
	v_add_f32_e32 v105, v104, v101
	v_sub_f32_e32 v106, v86, v105
	v_sub_f32_e32 v99, v86, v99
	v_sub_f32_e32 v86, v86, v106
	v_sub_f32_e32 v104, v105, v104
	v_sub_f32_e32 v84, v84, v99
	v_sub_f32_e32 v86, v86, v105
	v_sub_f32_e32 v101, v104, v101
	v_add_f32_e32 v84, v84, v86
	v_add_f32_e32 v84, v101, v84
	v_add_f32_e32 v86, v106, v84
	v_mul_f32_e32 v99, v103, v86
	v_mul_f32_e32 v104, v102, v99
	v_add_f32_e32 v101, v98, v99
	v_fma_f32 v102, v99, v102, -v104
	v_sub_f32_e32 v98, v101, v98
	v_fmac_f32_e32 v102, v99, v100
	v_sub_f32_e32 v98, v99, v98
	v_add_f32_e32 v99, v104, v102
	v_sub_f32_e32 v100, v86, v99
	v_sub_f32_e32 v104, v99, v104
	v_sub_f32_e32 v102, v104, v102
	v_sub_f32_e32 v104, v106, v86
	v_sub_f32_e32 v86, v86, v100
	v_add_f32_e32 v84, v84, v104
	v_sub_f32_e32 v86, v86, v99
	v_add_f32_e32 v84, v84, v86
	v_add_f32_e32 v84, v102, v84
	v_add_f32_e32 v84, v100, v84
	v_mul_f32_e32 v84, v103, v84
	v_add_f32_e32 v84, v98, v84
	v_add_f32_e32 v86, v101, v84
	v_mul_f32_e32 v99, v86, v86
	v_fmamk_f32 v102, v99, 0x3e9b6dac, v93
	v_mul_f32_e32 v100, v86, v99
	v_fmaak_f32 v99, v99, v102, 0x3f2aaada
	v_ldexp_f32 v98, v86, 1
	v_mul_f32_e32 v99, v100, v99
	v_mul_f32_e32 v64, 0x3fb8aa3b, v64
	v_add_f32_e32 v100, v98, v99
	v_sub_f32_e32 v86, v86, v101
	global_store_dword v[68:69], v64, off offset:192
	global_store_dword v[70:71], v64, off
	v_min_f32_e32 v64, 0, v87
	v_mul_f32_e32 v87, 0x3f317218, v85
	v_sub_f32_e32 v84, v84, v86
	v_sub_f32_e32 v86, v100, v98
	v_fma_f32 v89, v85, s12, -v87
	v_ldexp_f32 v84, v84, 1
	v_sub_f32_e32 v86, v99, v86
	v_fmac_f32_e32 v89, 0xb102e308, v85
	v_add_f32_e32 v84, v84, v86
	v_add_f32_e32 v85, v87, v89
	v_add_f32_e32 v86, v100, v84
	v_add_f32_e32 v98, v85, v86
	v_sub_f32_e32 v87, v85, v87
	v_sub_f32_e32 v87, v89, v87
	v_sub_f32_e32 v89, v86, v100
	v_sub_f32_e32 v99, v98, v85
	v_sub_f32_e32 v84, v84, v89
	v_sub_f32_e32 v86, v86, v99
	v_sub_f32_e32 v99, v98, v99
	v_add_f32_e32 v89, v87, v84
	v_sub_f32_e32 v85, v85, v99
	v_add_f32_e32 v85, v86, v85
	v_sub_f32_e32 v99, v89, v87
	v_add_f32_e32 v85, v89, v85
	v_sub_f32_e32 v89, v89, v99
	v_add_f32_e32 v86, v98, v85
	v_sub_f32_e32 v84, v84, v99
	v_sub_f32_e32 v87, v87, v89
	v_add_f32_e32 v84, v84, v87
	v_sub_f32_e32 v87, v86, v98
	v_sub_f32_e32 v85, v85, v87
	v_add_f32_e32 v82, v82, v97
; __device__ __forceinline__ void p1_side_task(int c, LAS unsigned char* lds, const bf16_t* XN, const bf16_t* WIN, const float* b_f, float* LF, bf16_t* Kb, bf16_t* Vb, bf16_t* P1b) {
;     ...
;             for (int j = 0; j < 4; ++j) { const float xx = acc[g][j] + bfh; const float v = (fminf(xx, 0.f) - log1pf(__expf(-fabsf(xx)))) * LOG2E; const int m = 4 * fq + j;
;                 if (g < 2) { const int row = 32 * c + 16 * g + m; LF[(size_t)((row >> 12) * NH + fr) * KVROWS + 64 + (row & 4095)] = v; }
;                 else if (c == 0) { LF[(size_t)fr * KVROWS + 48 + m] = v; LF[(size_t)(NH + fr) * KVROWS + 48 + m] = v; } }
	v_add_f32_e32 v84, v84, v85
	v_mul_f32_e64 v85, |v82|, s19
	v_add_f32_e32 v84, v86, v84
	v_cmp_neq_f32_e32 vcc, s33, v88
	v_exp_f32_e32 v86, v85
	s_nop 0
	v_cndmask_b32_e32 v84, v94, v84, vcc
	v_cmp_ngt_f32_e32 vcc, -1.0, v88
	v_add_f32_e32 v87, 1.0, v86
	v_add_f32_e32 v99, -1.0, v87
	v_cndmask_b32_e32 v84, v95, v84, vcc
	v_cmp_neq_f32_e32 vcc, -1.0, v88
	v_sub_f32_e32 v100, v86, v99
	s_nop 0
	v_cndmask_b32_e32 v84, v96, v84, vcc
	v_cmp_lt_f32_e64 vcc, |v88|, s23
	s_nop 1
	v_cndmask_b32_e32 v84, v84, v88, vcc
	v_sub_f32_e32 v64, v64, v84
	v_cvt_f64_f32_e32 v[84:85], v87
	v_frexp_exp_i32_f64_e32 v84, v[84:85]
	v_frexp_mant_f32_e32 v85, v87
	v_cmp_gt_f32_e32 vcc, s21, v85
	v_mul_f32_e32 v64, 0x3fb8aa3b, v64
	global_store_dword v[68:69], v64, off offset:196
	global_store_dword v[72:73], v64, off
	v_subbrev_co_u32_e32 v84, vcc, 0, v84, vcc
	v_cvt_f32_i32_e32 v85, v84
	v_sub_u32_e32 v84, 0, v84
	v_ldexp_f32 v89, v87, v84
	v_sub_f32_e32 v87, v99, v87
	v_add_f32_e32 v87, 1.0, v87
	v_add_f32_e32 v99, 1.0, v89
	v_add_f32_e32 v87, v100, v87
	v_add_f32_e32 v100, -1.0, v99
	v_ldexp_f32 v84, v87, v84
	v_sub_f32_e32 v100, v89, v100
	v_add_f32_e32 v100, v84, v100
	v_add_f32_e32 v98, -1.0, v89
	v_add_f32_e32 v101, v99, v100
	v_add_f32_e32 v87, 1.0, v98
	v_rcp_f32_e32 v102, v101
	v_sub_f32_e32 v87, v89, v87
	v_add_f32_e32 v84, v84, v87
	v_add_f32_e32 v87, v98, v84
	v_mul_f32_e32 v89, v87, v102
	v_mul_f32_e32 v103, v101, v89
	v_sub_f32_e32 v99, v101, v99
	v_sub_f32_e32 v99, v100, v99
	v_fma_f32 v100, v89, v101, -v103
	v_fmac_f32_e32 v100, v89, v99
	v_add_f32_e32 v104, v103, v100
	v_sub_f32_e32 v105, v87, v104
	v_sub_f32_e32 v98, v87, v98
	v_sub_f32_e32 v87, v87, v105
	v_sub_f32_e32 v103, v104, v103
	v_sub_f32_e32 v84, v84, v98
	v_sub_f32_e32 v87, v87, v104
	v_sub_f32_e32 v100, v103, v100
	v_add_f32_e32 v84, v84, v87
	v_add_f32_e32 v84, v100, v84
	v_add_f32_e32 v87, v105, v84
	v_mul_f32_e32 v98, v102, v87
	v_mul_f32_e32 v103, v101, v98
	v_add_f32_e32 v100, v89, v98
	v_fma_f32 v101, v98, v101, -v103
	v_sub_f32_e32 v89, v100, v89
	v_fmac_f32_e32 v101, v98, v99
	v_sub_f32_e32 v89, v98, v89
	v_add_f32_e32 v98, v103, v101
	v_sub_f32_e32 v99, v87, v98
	v_sub_f32_e32 v103, v98, v103
	v_sub_f32_e32 v101, v103, v101
	v_sub_f32_e32 v103, v105, v87
	v_sub_f32_e32 v87, v87, v99
	v_add_f32_e32 v84, v84, v103
	v_sub_f32_e32 v87, v87, v98
	v_add_f32_e32 v84, v84, v87
	v_add_f32_e32 v84, v101, v84
	v_add_f32_e32 v84, v99, v84
	v_mul_f32_e32 v84, v102, v84
	v_add_f32_e32 v84, v89, v84
	v_add_f32_e32 v87, v100, v84
	v_mul_f32_e32 v98, v87, v87
	v_fmamk_f32 v101, v98, 0x3e9b6dac, v93
	v_mul_f32_e32 v99, v87, v98
	v_fmaak_f32 v98, v98, v101, 0x3f2aaada
	v_ldexp_f32 v89, v87, 1
	v_mul_f32_e32 v98, v99, v98
	v_add_f32_e32 v99, v89, v98
	v_sub_f32_e32 v87, v87, v100
	v_min_f32_e32 v64, 0, v82
	v_mul_f32_e32 v82, 0x3f317218, v85
	v_sub_f32_e32 v84, v84, v87
	v_sub_f32_e32 v87, v99, v89
	v_fma_f32 v88, v85, s12, -v82
	v_ldexp_f32 v84, v84, 1
	v_sub_f32_e32 v87, v98, v87
	v_fmac_f32_e32 v88, 0xb102e308, v85
	v_add_f32_e32 v84, v84, v87
	v_add_f32_e32 v85, v82, v88
	v_add_f32_e32 v87, v99, v84
	v_add_f32_e32 v89, v85, v87
	v_sub_f32_e32 v82, v85, v82
	v_sub_f32_e32 v82, v88, v82
	v_sub_f32_e32 v88, v87, v99
	v_sub_f32_e32 v98, v89, v85
	v_sub_f32_e32 v84, v84, v88
	v_sub_f32_e32 v87, v87, v98
	v_sub_f32_e32 v98, v89, v98
	v_add_f32_e32 v88, v82, v84
	v_sub_f32_e32 v85, v85, v98
	v_add_f32_e32 v85, v87, v85
	v_sub_f32_e32 v98, v88, v82
	v_add_f32_e32 v85, v88, v85
	v_sub_f32_e32 v88, v88, v98
	v_add_f32_e32 v87, v89, v85
	v_sub_f32_e32 v84, v84, v98
	v_sub_f32_e32 v82, v82, v88
	v_add_f32_e32 v82, v84, v82
	v_sub_f32_e32 v84, v87, v89
	v_sub_f32_e32 v84, v85, v84
	v_add_f32_e32 v82, v82, v84
	v_add_f32_e32 v84, v83, v97
	v_mul_f32_e64 v83, |v84|, s19
	v_add_f32_e32 v82, v87, v82
	v_cmp_neq_f32_e32 vcc, s33, v86
	v_exp_f32_e32 v85, v83
	s_nop 0
	v_cndmask_b32_e32 v82, v94, v82, vcc
	v_cmp_ngt_f32_e32 vcc, -1.0, v86
	s_nop 1
; __device__ __forceinline__ void p1_side_task(int c, LAS unsigned char* lds, const bf16_t* XN, const bf16_t* WIN, const float* b_f, float* LF, bf16_t* Kb, bf16_t* Vb, bf16_t* P1b) {
;     ...
;             for (int j = 0; j < 4; ++j) { const float xx = acc[g][j] + bfh; const float v = (fminf(xx, 0.f) - log1pf(__expf(-fabsf(xx)))) * LOG2E; const int m = 4 * fq + j;
;                 if (g < 2) { const int row = 32 * c + 16 * g + m; LF[(size_t)((row >> 12) * NH + fr) * KVROWS + 64 + (row & 4095)] = v; }
;                 else if (c == 0) { LF[(size_t)fr * KVROWS + 48 + m] = v; LF[(size_t)(NH + fr) * KVROWS + 48 + m] = v; } }
	v_cndmask_b32_e32 v82, v95, v82, vcc
	v_cmp_neq_f32_e32 vcc, -1.0, v86
	s_nop 1
	v_cndmask_b32_e32 v82, v96, v82, vcc
	v_cmp_lt_f32_e64 vcc, |v86|, s23
	s_nop 1
	v_cndmask_b32_e32 v82, v82, v86, vcc
	v_add_f32_e32 v86, 1.0, v85
	v_sub_f32_e32 v64, v64, v82
	v_cvt_f64_f32_e32 v[82:83], v86
	v_frexp_exp_i32_f64_e32 v82, v[82:83]
	v_frexp_mant_f32_e32 v83, v86
	v_cmp_gt_f32_e32 vcc, s21, v83
	v_add_f32_e32 v97, -1.0, v86
	v_sub_f32_e32 v98, v85, v97
	v_subbrev_co_u32_e32 v82, vcc, 0, v82, vcc
	v_cvt_f32_i32_e32 v83, v82
	v_sub_u32_e32 v82, 0, v82
	v_ldexp_f32 v88, v86, v82
	v_sub_f32_e32 v86, v97, v86
	v_add_f32_e32 v86, 1.0, v86
	v_add_f32_e32 v97, 1.0, v88
	v_add_f32_e32 v86, v98, v86
	v_add_f32_e32 v98, -1.0, v97
	v_ldexp_f32 v82, v86, v82
	v_sub_f32_e32 v98, v88, v98
	v_add_f32_e32 v98, v82, v98
	v_add_f32_e32 v89, -1.0, v88
	v_add_f32_e32 v99, v97, v98
	v_add_f32_e32 v86, 1.0, v89
	v_rcp_f32_e32 v100, v99
	v_sub_f32_e32 v86, v88, v86
	v_add_f32_e32 v82, v82, v86
	v_add_f32_e32 v86, v89, v82
	v_mul_f32_e32 v88, v86, v100
	v_mul_f32_e32 v101, v99, v88
	v_sub_f32_e32 v97, v99, v97
	v_sub_f32_e32 v97, v98, v97
	v_fma_f32 v98, v88, v99, -v101
	v_fmac_f32_e32 v98, v88, v97
	v_add_f32_e32 v102, v101, v98
	v_sub_f32_e32 v103, v86, v102
	v_sub_f32_e32 v89, v86, v89
	v_sub_f32_e32 v86, v86, v103
	v_sub_f32_e32 v101, v102, v101
	v_sub_f32_e32 v82, v82, v89
	v_sub_f32_e32 v86, v86, v102
	v_sub_f32_e32 v98, v101, v98
	v_add_f32_e32 v82, v82, v86
	v_add_f32_e32 v82, v98, v82
	v_add_f32_e32 v86, v103, v82
	v_mul_f32_e32 v89, v100, v86
	v_mul_f32_e32 v101, v99, v89
	v_add_f32_e32 v98, v88, v89
	v_fma_f32 v99, v89, v99, -v101
	v_sub_f32_e32 v88, v98, v88
	v_fmac_f32_e32 v99, v89, v97
	v_sub_f32_e32 v88, v89, v88
	v_add_f32_e32 v89, v101, v99
	v_sub_f32_e32 v97, v86, v89
	v_sub_f32_e32 v101, v89, v101
	v_sub_f32_e32 v99, v101, v99
	v_sub_f32_e32 v101, v103, v86
	v_sub_f32_e32 v86, v86, v97
	v_add_f32_e32 v82, v82, v101
	v_sub_f32_e32 v86, v86, v89
	v_add_f32_e32 v82, v82, v86
	v_add_f32_e32 v82, v99, v82
	v_add_f32_e32 v82, v97, v82
	v_mul_f32_e32 v82, v100, v82
	v_add_f32_e32 v82, v88, v82
	v_add_f32_e32 v86, v98, v82
	v_mul_f32_e32 v89, v86, v86
	v_fmamk_f32 v99, v89, 0x3e9b6dac, v93
	v_mul_f32_e32 v97, v86, v89
	v_fmaak_f32 v89, v89, v99, 0x3f2aaada
	v_ldexp_f32 v88, v86, 1
	v_mul_f32_e32 v89, v97, v89
	v_mul_f32_e32 v64, 0x3fb8aa3b, v64
	v_add_f32_e32 v97, v88, v89
	v_sub_f32_e32 v86, v86, v98
	global_store_dword v[68:69], v64, off offset:200
	global_store_dword v[74:75], v64, off
	v_min_f32_e32 v64, 0, v84
	v_mul_f32_e32 v84, 0x3f317218, v83
	v_sub_f32_e32 v82, v82, v86
	v_sub_f32_e32 v86, v97, v88
	v_fma_f32 v87, v83, s12, -v84
	v_ldexp_f32 v82, v82, 1
	v_sub_f32_e32 v86, v89, v86
	v_fmac_f32_e32 v87, 0xb102e308, v83
	v_add_f32_e32 v82, v82, v86
	v_add_f32_e32 v83, v84, v87
	v_add_f32_e32 v86, v97, v82
	v_add_f32_e32 v88, v83, v86
	v_sub_f32_e32 v84, v83, v84
	v_sub_f32_e32 v84, v87, v84
	v_sub_f32_e32 v87, v86, v97
	v_sub_f32_e32 v89, v88, v83
	v_sub_f32_e32 v82, v82, v87
	v_sub_f32_e32 v86, v86, v89
	v_sub_f32_e32 v89, v88, v89
	v_add_f32_e32 v87, v84, v82
	v_sub_f32_e32 v83, v83, v89
	v_add_f32_e32 v83, v86, v83
	v_sub_f32_e32 v89, v87, v84
	v_add_f32_e32 v83, v87, v83
	v_sub_f32_e32 v87, v87, v89
	v_add_f32_e32 v86, v88, v83
	v_sub_f32_e32 v82, v82, v89
	v_sub_f32_e32 v84, v84, v87
	v_add_f32_e32 v82, v82, v84
	v_sub_f32_e32 v84, v86, v88
	v_sub_f32_e32 v83, v83, v84
	v_add_f32_e32 v82, v82, v83
	v_add_f32_e32 v82, v86, v82
	v_cmp_neq_f32_e32 vcc, s33, v85
	s_nop 1
	v_cndmask_b32_e32 v82, v94, v82, vcc
	v_cmp_ngt_f32_e32 vcc, -1.0, v85
	s_nop 1
	v_cndmask_b32_e32 v82, v95, v82, vcc
	v_cmp_neq_f32_e32 vcc, -1.0, v85
	s_nop 1
	v_cndmask_b32_e32 v82, v96, v82, vcc
	v_cmp_lt_f32_e64 vcc, |v85|, s23
	s_nop 1
	v_cndmask_b32_e32 v82, v82, v85, vcc
	v_sub_f32_e32 v64, v64, v82
	v_mul_f32_e32 v64, 0x3fb8aa3b, v64
	global_store_dword v[68:69], v64, off offset:204
	global_store_dword v[76:77], v64, off
